# v59 + P1 GELU tail: (pk_mul, pk_fma, 2 cmp, 2 cndmask) per pair replaced by 2 v_max + 2 v_fma o=fma(-|v|,t,max(v,0)) for 40 of 64 pairs (bit-identical)
# baseline (speedup 1.0000x reference)
.LBB0_223:
	v_lshl_add_u32 v164, s10, 8, v170
	v_ashrrev_i32_e32 v165, 31, v164
	v_or_b32_e32 v162, 16, v164
	v_lshlrev_b64 v[148:149], 6, v[164:165]
	v_ashrrev_i32_e32 v163, 31, v162
	v_or_b32_e32 v160, 32, v164
	v_lshl_add_u64 v[148:149], v[138:139], 0, v[148:149]
	v_lshlrev_b64 v[150:151], 6, v[162:163]
	v_ashrrev_i32_e32 v161, 31, v160
	v_or_b32_e32 v158, 48, v164
	v_lshl_add_u64 v[150:151], v[138:139], 0, v[150:151]
	global_load_dwordx4 v[166:169], v[148:149], off
	global_load_dwordx4 v[182:185], v[150:151], off
	v_lshlrev_b64 v[148:149], 6, v[160:161]
	v_ashrrev_i32_e32 v159, 31, v158
	v_lshl_add_u64 v[148:149], v[138:139], 0, v[148:149]
	v_lshlrev_b64 v[150:151], 6, v[158:159]
	v_lshl_add_u64 v[150:151], v[138:139], 0, v[150:151]
	global_load_dwordx4 v[186:189], v[148:149], off
	global_load_dwordx4 v[190:193], v[150:151], off
	v_add_u32_e32 v156, 0x80, v164
	v_ashrrev_i32_e32 v157, 31, v156
	v_lshlrev_b64 v[148:149], 6, v[156:157]
	v_add_u32_e32 v154, 0x90, v164
	v_lshl_add_u64 v[148:149], v[138:139], 0, v[148:149]
	v_ashrrev_i32_e32 v155, 31, v154
	global_load_dwordx4 v[194:197], v[148:149], off
	v_lshlrev_b64 v[148:149], 6, v[154:155]
	v_lshl_add_u64 v[148:149], v[138:139], 0, v[148:149]
	global_load_dwordx4 v[198:201], v[148:149], off
	v_and_b32_e32 v148, 64, v176
	v_xor_b32_e32 v137, 16, v176
	v_add_u32_e32 v151, 64, v148
	v_xor_b32_e32 v149, 32, v176
	v_add_u32_e32 v150, 0xa0, v164
	v_cmp_lt_i32_e32 vcc, v137, v151
	v_add_u32_e32 v148, 0xb0, v164
	s_cmp_gt_i32 s8, 7
	v_cndmask_b32_e32 v137, v176, v137, vcc
	v_cmp_lt_i32_e32 vcc, v149, v151
	v_ashrrev_i32_e32 v151, 31, v150
	v_lshlrev_b64 v[152:153], 6, v[150:151]
	v_lshl_add_u64 v[152:153], v[138:139], 0, v[152:153]
	global_load_dwordx4 v[204:207], v[152:153], off
	v_cndmask_b32_e32 v179, v176, v149, vcc
	v_ashrrev_i32_e32 v149, 31, v148
	v_lshlrev_b64 v[152:153], 6, v[148:149]
	v_lshl_add_u64 v[152:153], v[138:139], 0, v[152:153]
	global_load_dwordx4 v[208:211], v[152:153], off
	v_lshlrev_b32_e32 v180, 2, v137
	v_lshlrev_b32_e32 v179, 2, v179
	s_cselect_b64 s[10:11], -1, 0
	s_and_b64 s[50:51], s[10:11], exec
	s_cselect_b32 s20, -8, 0
	s_cselect_b32 s9, 0x8000000, 0
	s_add_i32 s20, s20, s8
	s_add_u32 s50, s58, s9
	s_addc_u32 s51, s59, 0
	s_cmp_lt_i32 s8, 8
	s_waitcnt vmcnt(0)
	v_mov_b32_e32 v152, v167
	v_mov_b32_e32 v153, v168
	v_mov_b32_e32 v167, v169
	v_pk_add_f32 v[152:153], v[152:153], v[166:167]
	v_add_f32_e32 v137, v182, v183
	v_add_f32_e32 v152, v152, v153
	v_add_f32_e32 v167, v186, v187
	v_add_f32_e32 v168, v188, v189
	v_add_f32_e32 v153, v167, v168
	v_mov_b32_e32 v168, v152
	v_add_f32_e32 v166, v184, v185
	v_add_f32_e32 v169, v190, v191
	v_add_f32_e32 v181, v192, v193
	v_add_f32_e32 v137, v137, v166
	s_waitcnt lgkmcnt(0)
	v_permlane16_swap_b32_e32 v152, v168
	v_add_f32_e32 v152, v152, v168
	v_add_f32_e32 v166, v169, v181
	v_mov_b32_e32 v181, v137
	v_mov_b32_e32 v168, v152
	v_add_f32_e32 v182, v194, v195
	v_add_f32_e32 v183, v196, v197
	v_add_f32_e32 v184, v198, v199
	s_waitcnt lgkmcnt(1)
	v_permlane16_swap_b32_e32 v137, v181
	v_add_f32_e32 v193, v137, v181
	s_waitcnt lgkmcnt(0)
	v_permlane32_swap_b32_e32 v152, v168
	v_add_f32_e32 v137, v152, v168
	v_fmamk_f32 v137, v137, 0x3a800000, v177
	v_add_f32_e32 v185, v200, v201
	v_add_f32_e32 v167, v182, v183
	v_mov_b32_e32 v182, v153
	v_add_f32_e32 v169, v184, v185
	v_mov_b32_e32 v183, v166
	v_mov_b32_e32 v184, v167
	s_waitcnt lgkmcnt(2)
	v_permlane16_swap_b32_e32 v153, v182
	v_add_f32_e32 v191, v153, v182
	v_mov_b64_e32 v[198:199], s[30:31]
	s_waitcnt lgkmcnt(1)
	v_permlane16_swap_b32_e32 v166, v183
	v_add_f32_e32 v189, v166, v183
	s_waitcnt lgkmcnt(0)
	v_permlane16_swap_b32_e32 v167, v184
	v_add_f32_e32 v187, v167, v184
	v_mov_b32_e32 v194, v193
	v_mov_b32_e32 v192, v191
	v_mov_b32_e32 v190, v189
	v_mov_b32_e32 v188, v187
	v_rsq_f32_e32 v168, v137
	s_nop 0
	v_pk_mul_f32 v[124:125], v[124:125], v[168:169] op_sel_hi:[1,0]
	v_add_f32_e32 v152, v204, v205
	v_and_b32_e32 v197, 0x7fffffff, v125
	v_and_b32_e32 v196, 0x7fffffff, v124
	v_pk_fma_f32 v[196:197], v[196:197], s[26:27], 1.0 op_sel_hi:[1,0,0]
	v_pk_mul_f32 v[204:205], v[124:125], v[124:125]
	v_rcp_f32_e32 v196, v196
	v_rcp_f32_e32 v197, v197
	v_pk_mul_f32 v[204:205], v[204:205], s[40:41] op_sel_hi:[1,0]
	v_pk_mul_f32 v[126:127], v[126:127], v[168:169] op_sel_hi:[1,0]
	v_exp_f32_e32 v204, v204
	v_pk_fma_f32 v[200:201], v[196:197], s[28:29], v[198:199] op_sel_hi:[1,0,0]
	v_exp_f32_e32 v205, v205
	v_pk_fma_f32 v[200:201], v[196:197], v[200:201], s[34:35] op_sel_hi:[1,1,0]
	v_mov_b32_e32 v137, v169
	v_add_f32_e32 v153, v206, v207
	v_pk_fma_f32 v[200:201], v[196:197], v[200:201], s[36:37] op_sel_hi:[1,1,0]
	v_and_b32_e32 v207, 0x7fffffff, v127
	v_and_b32_e32 v206, 0x7fffffff, v126
	v_pk_fma_f32 v[200:201], v[196:197], v[200:201], s[38:39] op_sel_hi:[1,1,0]
	v_pk_fma_f32 v[206:207], v[206:207], s[26:27], 1.0 op_sel_hi:[1,0,0]
	v_pk_mul_f32 v[196:197], v[196:197], v[200:201]
	v_rcp_f32_e32 v206, v206
	v_rcp_f32_e32 v207, v207
	v_pk_mul_f32 v[196:197], v[204:205], v[196:197]
	v_cmp_gt_f32_e32 vcc, 0, v124
	v_pk_mul_f32 v[204:205], v[124:125], v[196:197]
	v_pk_fma_f32 v[196:197], v[124:125], v[196:197], v[124:125] neg_lo:[1,0,0] neg_hi:[1,0,0]
	s_waitcnt lgkmcnt(0)
	v_permlane16_swap_b32_e32 v169, v137
	v_add_f32_e32 v185, v169, v137
	v_pk_mul_f32 v[200:201], v[126:127], v[126:127]
	v_cndmask_b32_e32 v137, v196, v204, vcc
	v_cmp_gt_f32_e32 vcc, 0, v125
	v_pk_mul_f32 v[122:123], v[122:123], v[168:169] op_sel_hi:[1,0]
	v_pk_mul_f32 v[120:121], v[120:121], v[168:169] op_sel_hi:[1,0]
	v_cndmask_b32_e32 v169, v197, v205, vcc
	v_pk_fma_f32 v[124:125], v[206:207], s[28:29], v[198:199] op_sel_hi:[1,0,0]
	v_pk_mul_f32 v[196:197], v[200:201], s[40:41] op_sel_hi:[1,0]
	v_pk_fma_f32 v[124:125], v[206:207], v[124:125], s[34:35] op_sel_hi:[1,1,0]
	v_exp_f32_e32 v196, v196
	v_exp_f32_e32 v197, v197
	v_pk_fma_f32 v[124:125], v[206:207], v[124:125], s[36:37] op_sel_hi:[1,1,0]
	v_and_b32_e32 v201, 0x7fffffff, v121
	v_and_b32_e32 v200, 0x7fffffff, v120
	v_pk_fma_f32 v[124:125], v[206:207], v[124:125], s[38:39] op_sel_hi:[1,1,0]
	v_pk_fma_f32 v[200:201], v[200:201], s[26:27], 1.0 op_sel_hi:[1,0,0]
	v_pk_mul_f32 v[124:125], v[206:207], v[124:125]
	v_rcp_f32_e32 v200, v200
	v_rcp_f32_e32 v201, v201
	v_pk_mul_f32 v[124:125], v[196:197], v[124:125]
	v_max_f32_e32 v195, 0, v126
	v_max_f32_e32 v204, 0, v127
	v_fma_f32 v195, -|v126|, v124, v195
	v_fma_f32 v204, -|v127|, v125, v204
	v_add_f32_e32 v166, v208, v209
	v_pk_mul_f32 v[126:127], v[120:121], v[120:121]
	v_add_f32_e32 v167, v210, v211
	v_pk_fma_f32 v[124:125], v[200:201], s[28:29], v[198:199] op_sel_hi:[1,0,0]
	v_pk_mul_f32 v[126:127], v[126:127], s[40:41] op_sel_hi:[1,0]
	v_pk_fma_f32 v[124:125], v[200:201], v[124:125], s[34:35] op_sel_hi:[1,1,0]
	v_exp_f32_e32 v126, v126
	v_pk_fma_f32 v[124:125], v[200:201], v[124:125], s[36:37] op_sel_hi:[1,1,0]
	v_exp_f32_e32 v127, v127
	v_pk_fma_f32 v[124:125], v[200:201], v[124:125], s[38:39] op_sel_hi:[1,1,0]
	v_add_f32_e32 v152, v152, v153
	v_pk_mul_f32 v[124:125], v[200:201], v[124:125]
	v_and_b32_e32 v201, 0x7fffffff, v123
	v_and_b32_e32 v200, 0x7fffffff, v122
	v_pk_fma_f32 v[200:201], v[200:201], s[26:27], 1.0 op_sel_hi:[1,0,0]
	v_pk_mul_f32 v[124:125], v[126:127], v[124:125]
	v_rcp_f32_e32 v200, v200
	v_rcp_f32_e32 v201, v201
	v_add_f32_e32 v166, v166, v167
	v_max_f32_e32 v126, 0, v120
	v_max_f32_e32 v127, 0, v121
	v_fma_f32 v126, -|v120|, v124, v126
	v_fma_f32 v127, -|v121|, v125, v127
	v_mov_b32_e32 v153, v152
	v_mov_b32_e32 v167, v166
	v_pk_mul_f32 v[196:197], v[122:123], v[122:123]
	v_pk_fma_f32 v[120:121], v[200:201], s[28:29], v[198:199] op_sel_hi:[1,0,0]
	s_waitcnt lgkmcnt(1)
	v_permlane16_swap_b32_e32 v152, v153
	v_add_f32_e32 v183, v152, v153
	v_pk_mul_f32 v[124:125], v[196:197], s[40:41] op_sel_hi:[1,0]
	v_pk_fma_f32 v[120:121], v[200:201], v[120:121], s[34:35] op_sel_hi:[1,1,0]
	v_exp_f32_e32 v124, v124
	v_exp_f32_e32 v125, v125
	v_pk_fma_f32 v[120:121], v[200:201], v[120:121], s[36:37] op_sel_hi:[1,1,0]
	s_waitcnt lgkmcnt(0)
	v_permlane16_swap_b32_e32 v166, v167
	v_add_f32_e32 v181, v166, v167
	v_pk_fma_f32 v[120:121], v[200:201], v[120:121], s[38:39] op_sel_hi:[1,1,0]
	v_mov_b32_e32 v186, v185
	v_pk_mul_f32 v[120:121], v[200:201], v[120:121]
	v_mov_b32_e32 v184, v183
	v_mov_b32_e32 v182, v181
	v_pk_mul_f32 v[120:121], v[124:125], v[120:121]
	v_lshl_or_b32 v152, s20, 8, v172
	v_pk_mul_f32 v[124:125], v[122:123], v[120:121]
	v_pk_fma_f32 v[120:121], v[122:123], v[120:121], v[122:123] neg_lo:[1,0,0] neg_hi:[1,0,0]
	v_cmp_gt_f32_e32 vcc, 0, v122
	v_ashrrev_i32_e32 v153, 31, v152
	v_lshl_add_u64 v[152:153], v[152:153], 1, s[50:51]
	v_cndmask_b32_e32 v124, v120, v124, vcc
	v_cmp_gt_f32_e32 vcc, 0, v123
	v_lshlrev_b64 v[166:167], 12, v[164:165]
	v_lshl_add_u64 v[166:167], v[152:153], 0, v[166:167]
	v_cndmask_b32_e32 v123, v121, v125, vcc
	v_cvt_pk_bf16_f32 v120, v137, v169
	v_cvt_pk_bf16_f32 v121, v195, v204
	v_cvt_pk_bf16_f32 v122, v126, v127
	v_cvt_pk_bf16_f32 v123, v124, v123
	v_mov_b32_e32 v124, 0
	v_mov_b32_e32 v125, 0
	global_store_dwordx4 v[166:167], v[120:123], off
	s_cbranch_scc1 .LBB0_225
	v_and_b32_e32 v125, 16, v120
	v_and_b32_e32 v124, 0xffff0000, v120
	v_lshlrev_b32_e32 v197, 16, v121
	v_lshlrev_b32_e32 v196, 16, v122
	v_and_b32_e32 v126, 0xffff0000, v121
	v_mov_b32_e32 v127, v124
	v_pk_mov_b32 v[204:205], v[196:197], v[124:125] op_sel:[1,0]
	v_lshlrev_b32_e32 v120, 16, v120
	v_and_b32_e32 v198, 0xffff0000, v123
	v_mov_b32_e32 v199, v126
	v_and_b32_e32 v122, 0xffff0000, v122
	v_lshlrev_b32_e32 v200, 16, v123
	v_mov_b32_e32 v123, v197
	v_mov_b32_e32 v121, v126
	v_mov_b32_e32 v201, v126
	v_pk_add_f32 v[206:207], v[126:127], v[204:205]
	v_pk_mul_f32 v[126:127], v[126:127], v[204:205]
	v_pk_add_f32 v[124:125], v[120:121], v[124:125] op_sel_hi:[0,1]
	v_mov_b32_e32 v207, v127
	v_pk_add_f32 v[126:127], v[196:197], v[122:123]
	v_pk_mul_f32 v[204:205], v[196:197], v[196:197]
	v_mov_b32_e32 v123, v198
	v_mul_f32_e32 v125, v120, v120
	v_mov_b32_e32 v127, v205
	v_pk_add_f32 v[204:205], v[198:199], v[200:201]
	v_pk_mul_f32 v[120:121], v[198:199], v[120:121]
	v_mov_b32_e32 v197, v200
	v_pk_mul_f32 v[122:123], v[122:123], v[122:123]
	v_mov_b32_e32 v205, v121
	v_pk_fma_f32 v[122:123], v[196:197], v[196:197], v[122:123]
	v_pk_add_f32 v[124:125], v[124:125], v[206:207]
	v_pk_add_f32 v[120:121], v[126:127], v[204:205]
	v_pk_add_f32 v[122:123], v[122:123], v[122:123] op_sel_hi:[0,1]
	v_pk_add_f32 v[120:121], v[124:125], v[120:121]
	v_mov_b32_e32 v137, v123
	v_pk_add_f32 v[124:125], v[120:121], v[136:137]
.LBB0_225:
	v_mov_b32_e32 v169, v168
	v_pk_mul_f32 v[116:117], v[116:117], v[168:169]
	v_mov_b32_e32 v120, v168
	v_and_b32_e32 v123, 0x7fffffff, v117
	v_and_b32_e32 v122, 0x7fffffff, v116
	v_pk_fma_f32 v[122:123], v[122:123], s[26:27], 1.0 op_sel_hi:[1,0,0]
	v_mov_b32_e32 v121, v168
	v_rcp_f32_e32 v122, v122
	v_rcp_f32_e32 v123, v123
	v_pk_mul_f32 v[118:119], v[118:119], v[120:121]
	v_pk_mul_f32 v[114:115], v[114:115], v[120:121]
	v_pk_mul_f32 v[112:113], v[112:113], v[168:169]
	v_mov_b64_e32 v[120:121], s[30:31]
	v_pk_mul_f32 v[168:169], v[116:117], v[116:117]
	v_pk_fma_f32 v[126:127], v[122:123], s[28:29], v[120:121] op_sel_hi:[1,0,0]
	v_pk_mul_f32 v[168:169], v[168:169], s[40:41] op_sel_hi:[1,0]
	v_pk_fma_f32 v[126:127], v[122:123], v[126:127], s[34:35] op_sel_hi:[1,1,0]
	v_exp_f32_e32 v168, v168
	v_exp_f32_e32 v169, v169
	v_pk_fma_f32 v[126:127], v[122:123], v[126:127], s[36:37] op_sel_hi:[1,1,0]
	v_and_b32_e32 v197, 0x7fffffff, v119
	v_and_b32_e32 v196, 0x7fffffff, v118
	v_pk_fma_f32 v[126:127], v[122:123], v[126:127], s[38:39] op_sel_hi:[1,1,0]
	v_pk_fma_f32 v[196:197], v[196:197], s[26:27], 1.0 op_sel_hi:[1,0,0]
	v_pk_mul_f32 v[122:123], v[122:123], v[126:127]
	v_rcp_f32_e32 v196, v196
	v_rcp_f32_e32 v197, v197
	v_pk_mul_f32 v[122:123], v[168:169], v[122:123]
	v_max_f32_e32 v137, 0, v116
	v_max_f32_e32 v168, 0, v117
	v_fma_f32 v137, -|v116|, v122, v137
	v_fma_f32 v168, -|v117|, v123, v168
	v_pk_mul_f32 v[126:127], v[118:119], v[118:119]
	v_pk_fma_f32 v[116:117], v[196:197], s[28:29], v[120:121] op_sel_hi:[1,0,0]
	s_lshl_b32 s8, s20, 3
	v_pk_mul_f32 v[122:123], v[126:127], s[40:41] op_sel_hi:[1,0]
	v_pk_fma_f32 v[116:117], v[196:197], v[116:117], s[34:35] op_sel_hi:[1,1,0]
	v_exp_f32_e32 v122, v122
	v_exp_f32_e32 v123, v123
	v_pk_fma_f32 v[116:117], v[196:197], v[116:117], s[36:37] op_sel_hi:[1,1,0]
	v_and_b32_e32 v127, 0x7fffffff, v113
	v_and_b32_e32 v126, 0x7fffffff, v112
	v_pk_fma_f32 v[116:117], v[196:197], v[116:117], s[38:39] op_sel_hi:[1,1,0]
	v_pk_fma_f32 v[126:127], v[126:127], s[26:27], 1.0 op_sel_hi:[1,0,0]
	v_pk_mul_f32 v[116:117], v[196:197], v[116:117]
	v_rcp_f32_e32 v126, v126
	v_rcp_f32_e32 v127, v127
	v_pk_mul_f32 v[116:117], v[122:123], v[116:117]
	v_max_f32_e32 v169, 0, v118
	v_max_f32_e32 v195, 0, v119
	v_fma_f32 v169, -|v118|, v116, v169
	v_fma_f32 v195, -|v119|, v117, v195
	s_or_b32 s50, s8, s62
	v_pk_mul_f32 v[118:119], v[112:113], v[112:113]
	s_ashr_i32 s51, s50, 31
	v_pk_fma_f32 v[116:117], v[126:127], s[28:29], v[120:121] op_sel_hi:[1,0,0]
	v_pk_mul_f32 v[118:119], v[118:119], s[40:41] op_sel_hi:[1,0]
	v_pk_fma_f32 v[116:117], v[126:127], v[116:117], s[34:35] op_sel_hi:[1,1,0]
	v_exp_f32_e32 v118, v118
	v_pk_fma_f32 v[116:117], v[126:127], v[116:117], s[36:37] op_sel_hi:[1,1,0]
	v_exp_f32_e32 v119, v119
	v_pk_fma_f32 v[116:117], v[126:127], v[116:117], s[38:39] op_sel_hi:[1,1,0]
	v_pk_mul_f32 v[116:117], v[126:127], v[116:117]
	v_and_b32_e32 v127, 0x7fffffff, v115
	v_and_b32_e32 v126, 0x7fffffff, v114
	v_pk_fma_f32 v[126:127], v[126:127], s[26:27], 1.0 op_sel_hi:[1,0,0]
	v_pk_mul_f32 v[116:117], v[118:119], v[116:117]
	v_rcp_f32_e32 v126, v126
	v_rcp_f32_e32 v127, v127
	v_max_f32_e32 v118, 0, v112
	v_max_f32_e32 v119, 0, v113
	v_fma_f32 v118, -|v112|, v116, v118
	v_fma_f32 v119, -|v113|, v117, v119
	v_pk_mul_f32 v[122:123], v[114:115], v[114:115]
	v_pk_fma_f32 v[112:113], v[126:127], s[28:29], v[120:121] op_sel_hi:[1,0,0]
	s_nop 0
	v_pk_mul_f32 v[116:117], v[122:123], s[40:41] op_sel_hi:[1,0]
	v_pk_fma_f32 v[112:113], v[126:127], v[112:113], s[34:35] op_sel_hi:[1,1,0]
	v_exp_f32_e32 v116, v116
	v_exp_f32_e32 v117, v117
	v_pk_fma_f32 v[112:113], v[126:127], v[112:113], s[36:37] op_sel_hi:[1,1,0]
	v_cmp_gt_f32_e32 vcc, 0, v114
	v_pk_fma_f32 v[112:113], v[126:127], v[112:113], s[38:39] op_sel_hi:[1,1,0]
	s_nop 0
	v_pk_mul_f32 v[112:113], v[126:127], v[112:113]
	s_nop 0
	v_pk_mul_f32 v[112:113], v[116:117], v[112:113]
	s_nop 0
	v_pk_mul_f32 v[116:117], v[114:115], v[112:113]
	v_pk_fma_f32 v[112:113], v[114:115], v[112:113], v[114:115] neg_lo:[1,0,0] neg_hi:[1,0,0]
	s_nop 0
	v_cndmask_b32_e32 v116, v112, v116, vcc
	v_cmp_gt_f32_e32 vcc, 0, v115
	v_cvt_pk_bf16_f32 v112, v137, v168
	s_nop 1
	v_cndmask_b32_e32 v115, v113, v117, vcc
	v_cvt_pk_bf16_f32 v113, v169, v195
	v_cvt_pk_bf16_f32 v114, v118, v119
	v_cvt_pk_bf16_f32 v115, v116, v115
	v_cndmask_b32_e64 v116, 0, 1, s[10:11]
	v_cmp_ne_u32_e64 s[8:9], 1, v116
	s_andn2_b64 vcc, exec, s[10:11]
	global_store_dwordx4 v[166:167], v[112:115], off offset:256
	s_cbranch_vccnz .LBB0_229
	v_lshlrev_b32_e32 v116, 16, v112
	v_and_b32_e32 v112, 0xffff0000, v112
	v_lshlrev_b32_e32 v118, 16, v113
	v_and_b32_e32 v120, 0xffff0000, v113
	v_lshlrev_b32_e32 v122, 16, v114
	v_and_b32_e32 v114, 0xffff0000, v114
	v_lshlrev_b32_e32 v126, 16, v115
	v_and_b32_e32 v166, 0xffff0000, v115
	v_mul_f32_e32 v117, v116, v116
	v_mul_f32_e32 v113, v112, v112
	v_mul_f32_e32 v119, v118, v118
	v_mul_f32_e32 v121, v120, v120
	v_mul_f32_e32 v123, v122, v122
	v_mul_f32_e32 v115, v114, v114
	v_mul_f32_e32 v127, v126, v126
	v_mul_f32_e32 v167, v166, v166
	v_pk_add_f32 v[112:113], v[116:117], v[112:113]
	v_pk_add_f32 v[116:117], v[118:119], v[120:121]
	v_pk_add_f32 v[114:115], v[122:123], v[114:115]
	v_pk_add_f32 v[112:113], v[112:113], v[116:117]
	v_pk_add_f32 v[116:117], v[126:127], v[166:167]
	s_nop 0
	v_pk_add_f32 v[114:115], v[114:115], v[116:117]
	s_nop 0
	v_pk_add_f32 v[112:113], v[112:113], v[114:115]
	s_nop 0
	v_pk_add_f32 v[112:113], v[124:125], v[112:113]
	s_nop 0
	v_mov_b32_e32 v114, v112
	v_mov_b32_e32 v115, v113
	s_nop 0
	v_permlane16_swap_b32_e32 v112, v114
	v_permlane16_swap_b32_e32 v113, v115
	v_pk_add_f32 v[112:113], v[112:113], v[114:115]
	s_nop 0
	v_mov_b32_e32 v114, v112
	v_mov_b32_e32 v115, v113
	s_nop 0
	v_permlane32_swap_b32_e32 v112, v114
	v_permlane32_swap_b32_e32 v113, v115
	v_pk_add_f32 v[112:113], v[112:113], v[114:115]
	s_and_saveexec_b64 s[10:11], s[4:5]
	s_cbranch_execz .LBB0_228
	v_lshlrev_b64 v[116:117], 8, v[164:165]
	v_lshl_add_u64 v[116:117], s[16:17], 0, v[116:117]
	v_lshl_add_u64 v[116:117], s[50:51], 2, v[116:117]
	global_store_dwordx2 v[116:117], v[112:113], off

.LBB0_229:
	s_nop 0
	s_nop 0
	v_permlane32_swap_b32_e32 v193, v194
	v_add_f32_e32 v112, v193, v194
	v_fmamk_f32 v112, v112, 0x3a800000, v177
	v_mov_b64_e32 v[118:119], s[30:31]
	s_waitcnt lgkmcnt(1)
	s_waitcnt lgkmcnt(0)
	v_rsq_f32_e32 v114, v112
	s_nop 0
	v_pk_mul_f32 v[108:109], v[108:109], v[114:115] op_sel_hi:[1,0]
	v_pk_mul_f32 v[110:111], v[110:111], v[114:115] op_sel_hi:[1,0]
	v_and_b32_e32 v117, 0x7fffffff, v109
	v_and_b32_e32 v116, 0x7fffffff, v108
	v_pk_fma_f32 v[116:117], v[116:117], s[26:27], 1.0 op_sel_hi:[1,0,0]
	v_pk_mul_f32 v[122:123], v[108:109], v[108:109]
	v_rcp_f32_e32 v116, v116
	v_rcp_f32_e32 v117, v117
	v_pk_mul_f32 v[122:123], v[122:123], s[40:41] op_sel_hi:[1,0]
	v_and_b32_e32 v125, 0x7fffffff, v111
	v_exp_f32_e32 v122, v122
	v_pk_fma_f32 v[120:121], v[116:117], s[28:29], v[118:119] op_sel_hi:[1,0,0]
	v_exp_f32_e32 v123, v123
	v_pk_fma_f32 v[120:121], v[116:117], v[120:121], s[34:35] op_sel_hi:[1,1,0]
	v_and_b32_e32 v124, 0x7fffffff, v110
	v_pk_fma_f32 v[120:121], v[116:117], v[120:121], s[36:37] op_sel_hi:[1,1,0]
	v_pk_fma_f32 v[124:125], v[124:125], s[26:27], 1.0 op_sel_hi:[1,0,0]
	v_pk_fma_f32 v[120:121], v[116:117], v[120:121], s[38:39] op_sel_hi:[1,1,0]
	v_rcp_f32_e32 v124, v124
	v_pk_mul_f32 v[116:117], v[116:117], v[120:121]
	v_rcp_f32_e32 v125, v125
	v_pk_mul_f32 v[116:117], v[122:123], v[116:117]
	v_cmp_gt_f32_e32 vcc, 0, v108
	v_pk_mul_f32 v[122:123], v[108:109], v[116:117]
	v_pk_fma_f32 v[116:117], v[108:109], v[116:117], v[108:109] neg_lo:[1,0,0] neg_hi:[1,0,0]
	v_pk_mul_f32 v[106:107], v[106:107], v[114:115] op_sel_hi:[1,0]
	v_pk_mul_f32 v[104:105], v[104:105], v[114:115] op_sel_hi:[1,0]
	v_pk_mul_f32 v[120:121], v[110:111], v[110:111]
	v_cndmask_b32_e32 v115, v116, v122, vcc
	v_cmp_gt_f32_e32 vcc, 0, v109
	v_pk_fma_f32 v[108:109], v[124:125], s[28:29], v[118:119] op_sel_hi:[1,0,0]
	v_lshlrev_b64 v[112:113], 12, v[162:163]
	v_cndmask_b32_e32 v122, v117, v123, vcc
	v_pk_mul_f32 v[116:117], v[120:121], s[40:41] op_sel_hi:[1,0]
	v_pk_fma_f32 v[108:109], v[124:125], v[108:109], s[34:35] op_sel_hi:[1,1,0]
	v_exp_f32_e32 v116, v116
	v_exp_f32_e32 v117, v117
	v_pk_fma_f32 v[108:109], v[124:125], v[108:109], s[36:37] op_sel_hi:[1,1,0]
	v_and_b32_e32 v121, 0x7fffffff, v105
	v_and_b32_e32 v120, 0x7fffffff, v104
	v_pk_fma_f32 v[108:109], v[124:125], v[108:109], s[38:39] op_sel_hi:[1,1,0]
	v_pk_fma_f32 v[120:121], v[120:121], s[26:27], 1.0 op_sel_hi:[1,0,0]
	v_pk_mul_f32 v[108:109], v[124:125], v[108:109]
	v_rcp_f32_e32 v120, v120
	v_rcp_f32_e32 v121, v121
	v_pk_mul_f32 v[108:109], v[116:117], v[108:109]
	v_max_f32_e32 v123, 0, v110
	v_max_f32_e32 v124, 0, v111
	v_fma_f32 v123, -|v110|, v108, v123
	v_fma_f32 v124, -|v111|, v109, v124
	v_lshl_add_u64 v[112:113], v[152:153], 0, v[112:113]
	v_pk_mul_f32 v[110:111], v[104:105], v[104:105]
	s_nop 0
	v_pk_fma_f32 v[108:109], v[120:121], s[28:29], v[118:119] op_sel_hi:[1,0,0]
	v_pk_mul_f32 v[110:111], v[110:111], s[40:41] op_sel_hi:[1,0]
	v_pk_fma_f32 v[108:109], v[120:121], v[108:109], s[34:35] op_sel_hi:[1,1,0]
	v_exp_f32_e32 v110, v110
	v_pk_fma_f32 v[108:109], v[120:121], v[108:109], s[36:37] op_sel_hi:[1,1,0]
	v_exp_f32_e32 v111, v111
	v_pk_fma_f32 v[108:109], v[120:121], v[108:109], s[38:39] op_sel_hi:[1,1,0]
	v_pk_mul_f32 v[108:109], v[120:121], v[108:109]
	v_and_b32_e32 v121, 0x7fffffff, v107
	v_and_b32_e32 v120, 0x7fffffff, v106
	v_pk_fma_f32 v[120:121], v[120:121], s[26:27], 1.0 op_sel_hi:[1,0,0]
	v_pk_mul_f32 v[108:109], v[110:111], v[108:109]
	v_rcp_f32_e32 v120, v120
	v_rcp_f32_e32 v121, v121
	v_max_f32_e32 v110, 0, v104
	v_max_f32_e32 v111, 0, v105
	v_fma_f32 v110, -|v104|, v108, v110
	v_fma_f32 v111, -|v105|, v109, v111
	v_pk_mul_f32 v[116:117], v[106:107], v[106:107]
	v_pk_fma_f32 v[104:105], v[120:121], s[28:29], v[118:119] op_sel_hi:[1,0,0]
	s_nop 0
	v_pk_mul_f32 v[108:109], v[116:117], s[40:41] op_sel_hi:[1,0]
	v_pk_fma_f32 v[104:105], v[120:121], v[104:105], s[34:35] op_sel_hi:[1,1,0]
	v_exp_f32_e32 v108, v108
	v_exp_f32_e32 v109, v109
	v_pk_fma_f32 v[104:105], v[120:121], v[104:105], s[36:37] op_sel_hi:[1,1,0]
	v_cmp_gt_f32_e32 vcc, 0, v106
	v_pk_fma_f32 v[104:105], v[120:121], v[104:105], s[38:39] op_sel_hi:[1,1,0]
	s_nop 0
	v_pk_mul_f32 v[104:105], v[120:121], v[104:105]
	s_nop 0
	v_pk_mul_f32 v[104:105], v[108:109], v[104:105]
	s_nop 0
	v_pk_mul_f32 v[108:109], v[106:107], v[104:105]
	v_pk_fma_f32 v[104:105], v[106:107], v[104:105], v[106:107] neg_lo:[1,0,0] neg_hi:[1,0,0]
	s_nop 0
	v_cndmask_b32_e32 v108, v104, v108, vcc
	v_cmp_gt_f32_e32 vcc, 0, v107
	v_cvt_pk_bf16_f32 v104, v115, v122
	s_nop 1
	v_cndmask_b32_e32 v107, v105, v109, vcc
	v_cvt_pk_bf16_f32 v105, v123, v124
	v_cvt_pk_bf16_f32 v106, v110, v111
	v_cvt_pk_bf16_f32 v107, v108, v107
	v_mov_b32_e32 v108, 0
	s_and_b64 vcc, exec, s[8:9]
	v_mov_b32_e32 v109, 0
	global_store_dwordx4 v[112:113], v[104:107], off
	s_cbranch_vccnz .LBB0_231
	v_and_b32_e32 v109, 16, v104
	v_and_b32_e32 v108, 0xffff0000, v104
	v_lshlrev_b32_e32 v117, 16, v105
	v_lshlrev_b32_e32 v116, 16, v106
	v_and_b32_e32 v110, 0xffff0000, v105
	v_mov_b32_e32 v111, v108
	v_pk_mov_b32 v[122:123], v[116:117], v[108:109] op_sel:[1,0]
	v_lshlrev_b32_e32 v104, 16, v104
	v_and_b32_e32 v118, 0xffff0000, v107
	v_mov_b32_e32 v119, v110
	v_and_b32_e32 v106, 0xffff0000, v106
	v_lshlrev_b32_e32 v120, 16, v107
	v_mov_b32_e32 v107, v117
	v_mov_b32_e32 v105, v110
	v_mov_b32_e32 v121, v110
	v_pk_add_f32 v[124:125], v[110:111], v[122:123]
	v_pk_mul_f32 v[110:111], v[110:111], v[122:123]
	v_pk_add_f32 v[108:109], v[104:105], v[108:109] op_sel_hi:[0,1]
	v_mov_b32_e32 v125, v111
	v_pk_add_f32 v[110:111], v[116:117], v[106:107]
	v_pk_mul_f32 v[122:123], v[116:117], v[116:117]
	v_mov_b32_e32 v107, v118
	v_mul_f32_e32 v109, v104, v104
	v_mov_b32_e32 v111, v123
	v_pk_add_f32 v[122:123], v[118:119], v[120:121]
	v_pk_mul_f32 v[104:105], v[118:119], v[104:105]
	v_mov_b32_e32 v117, v120
	v_pk_mul_f32 v[106:107], v[106:107], v[106:107]
	v_mov_b32_e32 v123, v105
	v_pk_fma_f32 v[106:107], v[116:117], v[116:117], v[106:107]
	v_pk_add_f32 v[108:109], v[108:109], v[124:125]
	v_pk_add_f32 v[104:105], v[110:111], v[122:123]
	v_pk_add_f32 v[106:107], v[106:107], v[106:107] op_sel_hi:[0,1]
	v_pk_add_f32 v[104:105], v[108:109], v[104:105]
	v_mov_b32_e32 v137, v107
	v_pk_add_f32 v[108:109], v[104:105], v[136:137]
.LBB0_231:
	v_mov_b32_e32 v115, v114
	v_pk_mul_f32 v[100:101], v[100:101], v[114:115]
	v_mov_b32_e32 v104, v114
	v_and_b32_e32 v107, 0x7fffffff, v101
	v_and_b32_e32 v106, 0x7fffffff, v100
	v_pk_fma_f32 v[106:107], v[106:107], s[26:27], 1.0 op_sel_hi:[1,0,0]
	v_mov_b32_e32 v105, v114
	v_rcp_f32_e32 v106, v106
	v_rcp_f32_e32 v107, v107
	v_pk_mul_f32 v[102:103], v[102:103], v[104:105]
	v_pk_mul_f32 v[98:99], v[98:99], v[104:105]
	v_pk_mul_f32 v[96:97], v[96:97], v[114:115]
	v_mov_b64_e32 v[104:105], s[30:31]
	v_pk_mul_f32 v[114:115], v[100:101], v[100:101]
	v_pk_fma_f32 v[110:111], v[106:107], s[28:29], v[104:105] op_sel_hi:[1,0,0]
	v_pk_mul_f32 v[114:115], v[114:115], s[40:41] op_sel_hi:[1,0]
	v_pk_fma_f32 v[110:111], v[106:107], v[110:111], s[34:35] op_sel_hi:[1,1,0]
	v_exp_f32_e32 v114, v114
	v_exp_f32_e32 v115, v115
	v_pk_fma_f32 v[110:111], v[106:107], v[110:111], s[36:37] op_sel_hi:[1,1,0]
	v_and_b32_e32 v117, 0x7fffffff, v103
	v_and_b32_e32 v116, 0x7fffffff, v102
	v_pk_fma_f32 v[110:111], v[106:107], v[110:111], s[38:39] op_sel_hi:[1,1,0]
	v_pk_fma_f32 v[116:117], v[116:117], s[26:27], 1.0 op_sel_hi:[1,0,0]
	v_pk_mul_f32 v[106:107], v[106:107], v[110:111]
	v_rcp_f32_e32 v116, v116
	v_rcp_f32_e32 v117, v117
	v_pk_mul_f32 v[106:107], v[114:115], v[106:107]
	v_max_f32_e32 v114, 0, v100
	v_max_f32_e32 v115, 0, v101
	v_fma_f32 v114, -|v100|, v106, v114
	v_fma_f32 v115, -|v101|, v107, v115
	v_pk_mul_f32 v[110:111], v[102:103], v[102:103]
	v_pk_fma_f32 v[100:101], v[116:117], s[28:29], v[104:105] op_sel_hi:[1,0,0]
	s_nop 0
	v_pk_mul_f32 v[106:107], v[110:111], s[40:41] op_sel_hi:[1,0]
	v_pk_fma_f32 v[100:101], v[116:117], v[100:101], s[34:35] op_sel_hi:[1,1,0]
	v_exp_f32_e32 v106, v106
	v_exp_f32_e32 v107, v107
	v_pk_fma_f32 v[100:101], v[116:117], v[100:101], s[36:37] op_sel_hi:[1,1,0]
	v_and_b32_e32 v111, 0x7fffffff, v97
	v_and_b32_e32 v110, 0x7fffffff, v96
	v_pk_fma_f32 v[100:101], v[116:117], v[100:101], s[38:39] op_sel_hi:[1,1,0]
	v_pk_fma_f32 v[110:111], v[110:111], s[26:27], 1.0 op_sel_hi:[1,0,0]
	v_pk_mul_f32 v[100:101], v[116:117], v[100:101]
	v_rcp_f32_e32 v110, v110
	v_rcp_f32_e32 v111, v111
	v_pk_mul_f32 v[100:101], v[106:107], v[100:101]
	v_max_f32_e32 v116, 0, v102
	v_max_f32_e32 v117, 0, v103
	v_fma_f32 v116, -|v102|, v100, v116
	v_fma_f32 v117, -|v103|, v101, v117
	s_nop 0
	v_pk_mul_f32 v[102:103], v[96:97], v[96:97]
	s_nop 0
	v_pk_fma_f32 v[100:101], v[110:111], s[28:29], v[104:105] op_sel_hi:[1,0,0]
	v_pk_mul_f32 v[102:103], v[102:103], s[40:41] op_sel_hi:[1,0]
	v_pk_fma_f32 v[100:101], v[110:111], v[100:101], s[34:35] op_sel_hi:[1,1,0]
	v_exp_f32_e32 v102, v102
	v_pk_fma_f32 v[100:101], v[110:111], v[100:101], s[36:37] op_sel_hi:[1,1,0]
	v_exp_f32_e32 v103, v103
	v_pk_fma_f32 v[100:101], v[110:111], v[100:101], s[38:39] op_sel_hi:[1,1,0]
	v_pk_mul_f32 v[100:101], v[110:111], v[100:101]
	v_and_b32_e32 v111, 0x7fffffff, v99
	v_and_b32_e32 v110, 0x7fffffff, v98
	v_pk_fma_f32 v[110:111], v[110:111], s[26:27], 1.0 op_sel_hi:[1,0,0]
	v_pk_mul_f32 v[100:101], v[102:103], v[100:101]
	v_rcp_f32_e32 v110, v110
	v_rcp_f32_e32 v111, v111
	v_max_f32_e32 v102, 0, v96
	v_max_f32_e32 v103, 0, v97
	v_fma_f32 v102, -|v96|, v100, v102
	v_fma_f32 v103, -|v97|, v101, v103
	v_pk_mul_f32 v[106:107], v[98:99], v[98:99]
	v_pk_fma_f32 v[96:97], v[110:111], s[28:29], v[104:105] op_sel_hi:[1,0,0]
	s_nop 0
	v_pk_mul_f32 v[100:101], v[106:107], s[40:41] op_sel_hi:[1,0]
	v_pk_fma_f32 v[96:97], v[110:111], v[96:97], s[34:35] op_sel_hi:[1,1,0]
	v_exp_f32_e32 v100, v100
	v_exp_f32_e32 v101, v101
	v_pk_fma_f32 v[96:97], v[110:111], v[96:97], s[36:37] op_sel_hi:[1,1,0]
	v_cmp_gt_f32_e32 vcc, 0, v98
	v_pk_fma_f32 v[96:97], v[110:111], v[96:97], s[38:39] op_sel_hi:[1,1,0]
	s_nop 0
	v_pk_mul_f32 v[96:97], v[110:111], v[96:97]
	s_nop 0
	v_pk_mul_f32 v[96:97], v[100:101], v[96:97]
	s_nop 0
	v_pk_mul_f32 v[100:101], v[98:99], v[96:97]
	v_pk_fma_f32 v[96:97], v[98:99], v[96:97], v[98:99] neg_lo:[1,0,0] neg_hi:[1,0,0]
	s_nop 0
	v_cndmask_b32_e32 v100, v96, v100, vcc
	v_cmp_gt_f32_e32 vcc, 0, v99
	v_cvt_pk_bf16_f32 v96, v114, v115
	s_nop 1
	v_cndmask_b32_e32 v99, v97, v101, vcc
	s_and_b64 vcc, exec, s[8:9]
	v_cvt_pk_bf16_f32 v97, v116, v117
	v_cvt_pk_bf16_f32 v98, v102, v103
	v_cvt_pk_bf16_f32 v99, v100, v99
	global_store_dwordx4 v[112:113], v[96:99], off offset:256
	s_cbranch_vccnz .LBB0_235
	v_lshlrev_b32_e32 v100, 16, v96
	v_and_b32_e32 v96, 0xffff0000, v96
	v_lshlrev_b32_e32 v102, 16, v97
	v_and_b32_e32 v104, 0xffff0000, v97
	v_lshlrev_b32_e32 v106, 16, v98
	v_and_b32_e32 v98, 0xffff0000, v98
	v_lshlrev_b32_e32 v110, 16, v99
	v_and_b32_e32 v112, 0xffff0000, v99
	v_mul_f32_e32 v101, v100, v100
	v_mul_f32_e32 v97, v96, v96
	v_mul_f32_e32 v103, v102, v102
	v_mul_f32_e32 v105, v104, v104
	v_mul_f32_e32 v107, v106, v106
	v_mul_f32_e32 v99, v98, v98
	v_mul_f32_e32 v111, v110, v110
	v_mul_f32_e32 v113, v112, v112
	v_pk_add_f32 v[96:97], v[100:101], v[96:97]
	v_pk_add_f32 v[100:101], v[102:103], v[104:105]
	v_pk_add_f32 v[98:99], v[106:107], v[98:99]
	v_pk_add_f32 v[96:97], v[96:97], v[100:101]
	v_pk_add_f32 v[100:101], v[110:111], v[112:113]
	s_nop 0
	v_pk_add_f32 v[98:99], v[98:99], v[100:101]
	s_nop 0
	v_pk_add_f32 v[96:97], v[96:97], v[98:99]
	s_nop 0
	v_pk_add_f32 v[96:97], v[108:109], v[96:97]
	s_nop 0
	v_mov_b32_e32 v98, v96
	v_mov_b32_e32 v99, v97
	s_nop 0
	v_permlane16_swap_b32_e32 v96, v98
	v_permlane16_swap_b32_e32 v97, v99
	v_pk_add_f32 v[96:97], v[96:97], v[98:99]
	s_nop 0
	v_mov_b32_e32 v98, v96
	v_mov_b32_e32 v99, v97
	s_nop 0
	v_permlane32_swap_b32_e32 v96, v98
	v_permlane32_swap_b32_e32 v97, v99
	v_pk_add_f32 v[96:97], v[96:97], v[98:99]
	s_and_saveexec_b64 s[10:11], s[4:5]
	s_cbranch_execz .LBB0_234
	v_lshlrev_b64 v[100:101], 8, v[162:163]
	v_lshl_add_u64 v[100:101], s[16:17], 0, v[100:101]
	v_lshl_add_u64 v[100:101], s[50:51], 2, v[100:101]
	global_store_dwordx2 v[100:101], v[96:97], off

.LBB0_235:
	s_nop 0
	s_nop 0
	v_permlane32_swap_b32_e32 v191, v192
	v_add_f32_e32 v96, v191, v192
	v_fmamk_f32 v96, v96, 0x3a800000, v177
	v_mov_b64_e32 v[102:103], s[30:31]
	s_waitcnt lgkmcnt(1)
	s_waitcnt lgkmcnt(0)
	v_rsq_f32_e32 v98, v96
	s_nop 0
	v_pk_mul_f32 v[92:93], v[92:93], v[98:99] op_sel_hi:[1,0]
	v_pk_mul_f32 v[94:95], v[94:95], v[98:99] op_sel_hi:[1,0]
	v_and_b32_e32 v101, 0x7fffffff, v93
	v_and_b32_e32 v100, 0x7fffffff, v92
	v_pk_fma_f32 v[100:101], v[100:101], s[26:27], 1.0 op_sel_hi:[1,0,0]
	v_pk_mul_f32 v[106:107], v[92:93], v[92:93]
	v_rcp_f32_e32 v100, v100
	v_rcp_f32_e32 v101, v101
	v_pk_mul_f32 v[106:107], v[106:107], s[40:41] op_sel_hi:[1,0]
	v_and_b32_e32 v109, 0x7fffffff, v95
	v_exp_f32_e32 v106, v106
	v_pk_fma_f32 v[104:105], v[100:101], s[28:29], v[102:103] op_sel_hi:[1,0,0]
	v_exp_f32_e32 v107, v107
	v_pk_fma_f32 v[104:105], v[100:101], v[104:105], s[34:35] op_sel_hi:[1,1,0]
	v_and_b32_e32 v108, 0x7fffffff, v94
	v_pk_fma_f32 v[104:105], v[100:101], v[104:105], s[36:37] op_sel_hi:[1,1,0]
	v_pk_fma_f32 v[108:109], v[108:109], s[26:27], 1.0 op_sel_hi:[1,0,0]
	v_pk_fma_f32 v[104:105], v[100:101], v[104:105], s[38:39] op_sel_hi:[1,1,0]
	v_rcp_f32_e32 v108, v108
	v_pk_mul_f32 v[100:101], v[100:101], v[104:105]
	v_rcp_f32_e32 v109, v109
	v_pk_mul_f32 v[100:101], v[106:107], v[100:101]
	v_cmp_gt_f32_e32 vcc, 0, v92
	v_pk_mul_f32 v[106:107], v[92:93], v[100:101]
	v_pk_fma_f32 v[100:101], v[92:93], v[100:101], v[92:93] neg_lo:[1,0,0] neg_hi:[1,0,0]
	v_pk_mul_f32 v[90:91], v[90:91], v[98:99] op_sel_hi:[1,0]
	v_pk_mul_f32 v[88:89], v[88:89], v[98:99] op_sel_hi:[1,0]
	v_pk_mul_f32 v[104:105], v[94:95], v[94:95]
	v_cndmask_b32_e32 v99, v100, v106, vcc
	v_cmp_gt_f32_e32 vcc, 0, v93
	v_pk_fma_f32 v[92:93], v[108:109], s[28:29], v[102:103] op_sel_hi:[1,0,0]
	v_lshlrev_b64 v[96:97], 12, v[160:161]
	v_cndmask_b32_e32 v106, v101, v107, vcc
	v_pk_mul_f32 v[100:101], v[104:105], s[40:41] op_sel_hi:[1,0]
	v_pk_fma_f32 v[92:93], v[108:109], v[92:93], s[34:35] op_sel_hi:[1,1,0]
	v_exp_f32_e32 v100, v100
	v_exp_f32_e32 v101, v101
	v_pk_fma_f32 v[92:93], v[108:109], v[92:93], s[36:37] op_sel_hi:[1,1,0]
	v_and_b32_e32 v105, 0x7fffffff, v89
	v_and_b32_e32 v104, 0x7fffffff, v88
	v_pk_fma_f32 v[92:93], v[108:109], v[92:93], s[38:39] op_sel_hi:[1,1,0]
	v_pk_fma_f32 v[104:105], v[104:105], s[26:27], 1.0 op_sel_hi:[1,0,0]
	v_pk_mul_f32 v[92:93], v[108:109], v[92:93]
	v_rcp_f32_e32 v104, v104
	v_rcp_f32_e32 v105, v105
	v_pk_mul_f32 v[92:93], v[100:101], v[92:93]
	v_max_f32_e32 v107, 0, v94
	v_max_f32_e32 v108, 0, v95
	v_fma_f32 v107, -|v94|, v92, v107
	v_fma_f32 v108, -|v95|, v93, v108
	v_lshl_add_u64 v[96:97], v[152:153], 0, v[96:97]
	v_pk_mul_f32 v[94:95], v[88:89], v[88:89]
	s_nop 0
	v_pk_fma_f32 v[92:93], v[104:105], s[28:29], v[102:103] op_sel_hi:[1,0,0]
	v_pk_mul_f32 v[94:95], v[94:95], s[40:41] op_sel_hi:[1,0]
	v_pk_fma_f32 v[92:93], v[104:105], v[92:93], s[34:35] op_sel_hi:[1,1,0]
	v_exp_f32_e32 v94, v94
	v_pk_fma_f32 v[92:93], v[104:105], v[92:93], s[36:37] op_sel_hi:[1,1,0]
	v_exp_f32_e32 v95, v95
	v_pk_fma_f32 v[92:93], v[104:105], v[92:93], s[38:39] op_sel_hi:[1,1,0]
	v_pk_mul_f32 v[92:93], v[104:105], v[92:93]
	v_and_b32_e32 v105, 0x7fffffff, v91
	v_and_b32_e32 v104, 0x7fffffff, v90
	v_pk_fma_f32 v[104:105], v[104:105], s[26:27], 1.0 op_sel_hi:[1,0,0]
	v_pk_mul_f32 v[92:93], v[94:95], v[92:93]
	v_rcp_f32_e32 v104, v104
	v_rcp_f32_e32 v105, v105
	v_max_f32_e32 v94, 0, v88
	v_max_f32_e32 v95, 0, v89
	v_fma_f32 v94, -|v88|, v92, v94
	v_fma_f32 v95, -|v89|, v93, v95
	v_pk_mul_f32 v[100:101], v[90:91], v[90:91]
	v_pk_fma_f32 v[88:89], v[104:105], s[28:29], v[102:103] op_sel_hi:[1,0,0]
	s_nop 0
	v_pk_mul_f32 v[92:93], v[100:101], s[40:41] op_sel_hi:[1,0]
	v_pk_fma_f32 v[88:89], v[104:105], v[88:89], s[34:35] op_sel_hi:[1,1,0]
	v_exp_f32_e32 v92, v92
	v_exp_f32_e32 v93, v93
	v_pk_fma_f32 v[88:89], v[104:105], v[88:89], s[36:37] op_sel_hi:[1,1,0]
	v_cmp_gt_f32_e32 vcc, 0, v90
	v_pk_fma_f32 v[88:89], v[104:105], v[88:89], s[38:39] op_sel_hi:[1,1,0]
	s_nop 0
	v_pk_mul_f32 v[88:89], v[104:105], v[88:89]
	s_nop 0
	v_pk_mul_f32 v[88:89], v[92:93], v[88:89]
	s_nop 0
	v_pk_mul_f32 v[92:93], v[90:91], v[88:89]
	v_pk_fma_f32 v[88:89], v[90:91], v[88:89], v[90:91] neg_lo:[1,0,0] neg_hi:[1,0,0]
	s_nop 0
	v_cndmask_b32_e32 v92, v88, v92, vcc
	v_cmp_gt_f32_e32 vcc, 0, v91
	v_cvt_pk_bf16_f32 v88, v99, v106
	s_nop 1
	v_cndmask_b32_e32 v91, v89, v93, vcc
	v_cvt_pk_bf16_f32 v89, v107, v108
	v_cvt_pk_bf16_f32 v90, v94, v95
	v_cvt_pk_bf16_f32 v91, v92, v91
	v_mov_b32_e32 v92, 0
	s_and_b64 vcc, exec, s[8:9]
	v_mov_b32_e32 v93, 0
	global_store_dwordx4 v[96:97], v[88:91], off
	s_cbranch_vccnz .LBB0_237
	v_and_b32_e32 v93, 16, v88
	v_and_b32_e32 v92, 0xffff0000, v88
	v_lshlrev_b32_e32 v101, 16, v89
	v_lshlrev_b32_e32 v100, 16, v90
	v_and_b32_e32 v94, 0xffff0000, v89
	v_mov_b32_e32 v95, v92
	v_pk_mov_b32 v[106:107], v[100:101], v[92:93] op_sel:[1,0]
	v_lshlrev_b32_e32 v88, 16, v88
	v_and_b32_e32 v102, 0xffff0000, v91
	v_mov_b32_e32 v103, v94
	v_and_b32_e32 v90, 0xffff0000, v90
	v_lshlrev_b32_e32 v104, 16, v91
	v_mov_b32_e32 v91, v101
	v_mov_b32_e32 v89, v94
	v_mov_b32_e32 v105, v94
	v_pk_add_f32 v[108:109], v[94:95], v[106:107]
	v_pk_mul_f32 v[94:95], v[94:95], v[106:107]
	v_pk_add_f32 v[92:93], v[88:89], v[92:93] op_sel_hi:[0,1]
	v_mov_b32_e32 v109, v95
	v_pk_add_f32 v[94:95], v[100:101], v[90:91]
	v_pk_mul_f32 v[106:107], v[100:101], v[100:101]
	v_mov_b32_e32 v91, v102
	v_mul_f32_e32 v93, v88, v88
	v_mov_b32_e32 v95, v107
	v_pk_add_f32 v[106:107], v[102:103], v[104:105]
	v_pk_mul_f32 v[88:89], v[102:103], v[88:89]
	v_mov_b32_e32 v101, v104
	v_pk_mul_f32 v[90:91], v[90:91], v[90:91]
	v_mov_b32_e32 v107, v89
	v_pk_fma_f32 v[90:91], v[100:101], v[100:101], v[90:91]
	v_pk_add_f32 v[92:93], v[92:93], v[108:109]
	v_pk_add_f32 v[88:89], v[94:95], v[106:107]
	v_pk_add_f32 v[90:91], v[90:91], v[90:91] op_sel_hi:[0,1]
	v_pk_add_f32 v[88:89], v[92:93], v[88:89]
	v_mov_b32_e32 v137, v91
	v_pk_add_f32 v[92:93], v[88:89], v[136:137]
.LBB0_237:
	v_mov_b32_e32 v99, v98
	v_pk_mul_f32 v[84:85], v[84:85], v[98:99]
	v_mov_b32_e32 v88, v98
	v_and_b32_e32 v91, 0x7fffffff, v85
	v_and_b32_e32 v90, 0x7fffffff, v84
	v_pk_fma_f32 v[90:91], v[90:91], s[26:27], 1.0 op_sel_hi:[1,0,0]
	v_mov_b32_e32 v89, v98
	v_rcp_f32_e32 v90, v90
	v_rcp_f32_e32 v91, v91
	v_pk_mul_f32 v[86:87], v[86:87], v[88:89]
	v_pk_mul_f32 v[82:83], v[82:83], v[88:89]
	v_pk_mul_f32 v[80:81], v[80:81], v[98:99]
	v_mov_b64_e32 v[88:89], s[30:31]
	v_pk_mul_f32 v[98:99], v[84:85], v[84:85]
	v_pk_fma_f32 v[94:95], v[90:91], s[28:29], v[88:89] op_sel_hi:[1,0,0]
	v_pk_mul_f32 v[98:99], v[98:99], s[40:41] op_sel_hi:[1,0]
	v_pk_fma_f32 v[94:95], v[90:91], v[94:95], s[34:35] op_sel_hi:[1,1,0]
	v_exp_f32_e32 v98, v98
	v_exp_f32_e32 v99, v99
	v_pk_fma_f32 v[94:95], v[90:91], v[94:95], s[36:37] op_sel_hi:[1,1,0]
	v_and_b32_e32 v101, 0x7fffffff, v87
	v_and_b32_e32 v100, 0x7fffffff, v86
	v_pk_fma_f32 v[94:95], v[90:91], v[94:95], s[38:39] op_sel_hi:[1,1,0]
	v_pk_fma_f32 v[100:101], v[100:101], s[26:27], 1.0 op_sel_hi:[1,0,0]
	v_pk_mul_f32 v[90:91], v[90:91], v[94:95]
	v_rcp_f32_e32 v100, v100
	v_rcp_f32_e32 v101, v101
	v_pk_mul_f32 v[90:91], v[98:99], v[90:91]
	v_max_f32_e32 v98, 0, v84
	v_max_f32_e32 v99, 0, v85
	v_fma_f32 v98, -|v84|, v90, v98
	v_fma_f32 v99, -|v85|, v91, v99
	v_pk_mul_f32 v[94:95], v[86:87], v[86:87]
	v_pk_fma_f32 v[84:85], v[100:101], s[28:29], v[88:89] op_sel_hi:[1,0,0]
	s_nop 0
	v_pk_mul_f32 v[90:91], v[94:95], s[40:41] op_sel_hi:[1,0]
	v_pk_fma_f32 v[84:85], v[100:101], v[84:85], s[34:35] op_sel_hi:[1,1,0]
	v_exp_f32_e32 v90, v90
	v_exp_f32_e32 v91, v91
	v_pk_fma_f32 v[84:85], v[100:101], v[84:85], s[36:37] op_sel_hi:[1,1,0]
	v_and_b32_e32 v95, 0x7fffffff, v81
	v_and_b32_e32 v94, 0x7fffffff, v80
	v_pk_fma_f32 v[84:85], v[100:101], v[84:85], s[38:39] op_sel_hi:[1,1,0]
	v_pk_fma_f32 v[94:95], v[94:95], s[26:27], 1.0 op_sel_hi:[1,0,0]
	v_pk_mul_f32 v[84:85], v[100:101], v[84:85]
	v_rcp_f32_e32 v94, v94
	v_rcp_f32_e32 v95, v95
	v_pk_mul_f32 v[84:85], v[90:91], v[84:85]
	v_max_f32_e32 v100, 0, v86
	v_max_f32_e32 v101, 0, v87
	v_fma_f32 v100, -|v86|, v84, v100
	v_fma_f32 v101, -|v87|, v85, v101
	s_nop 0
	v_pk_mul_f32 v[86:87], v[80:81], v[80:81]
	s_nop 0
	v_pk_fma_f32 v[84:85], v[94:95], s[28:29], v[88:89] op_sel_hi:[1,0,0]
	v_pk_mul_f32 v[86:87], v[86:87], s[40:41] op_sel_hi:[1,0]
	v_pk_fma_f32 v[84:85], v[94:95], v[84:85], s[34:35] op_sel_hi:[1,1,0]
	v_exp_f32_e32 v86, v86
	v_pk_fma_f32 v[84:85], v[94:95], v[84:85], s[36:37] op_sel_hi:[1,1,0]
	v_exp_f32_e32 v87, v87
	v_pk_fma_f32 v[84:85], v[94:95], v[84:85], s[38:39] op_sel_hi:[1,1,0]
	v_pk_mul_f32 v[84:85], v[94:95], v[84:85]
	v_and_b32_e32 v95, 0x7fffffff, v83
	v_and_b32_e32 v94, 0x7fffffff, v82
	v_pk_fma_f32 v[94:95], v[94:95], s[26:27], 1.0 op_sel_hi:[1,0,0]
	v_pk_mul_f32 v[84:85], v[86:87], v[84:85]
	v_rcp_f32_e32 v94, v94
	v_rcp_f32_e32 v95, v95
	v_max_f32_e32 v86, 0, v80
	v_max_f32_e32 v87, 0, v81
	v_fma_f32 v86, -|v80|, v84, v86
	v_fma_f32 v87, -|v81|, v85, v87
	v_pk_mul_f32 v[90:91], v[82:83], v[82:83]
	v_pk_fma_f32 v[80:81], v[94:95], s[28:29], v[88:89] op_sel_hi:[1,0,0]
	s_nop 0
	v_pk_mul_f32 v[84:85], v[90:91], s[40:41] op_sel_hi:[1,0]
	v_pk_fma_f32 v[80:81], v[94:95], v[80:81], s[34:35] op_sel_hi:[1,1,0]
	v_exp_f32_e32 v84, v84
	v_exp_f32_e32 v85, v85
	v_pk_fma_f32 v[80:81], v[94:95], v[80:81], s[36:37] op_sel_hi:[1,1,0]
	v_cmp_gt_f32_e32 vcc, 0, v82
	v_pk_fma_f32 v[80:81], v[94:95], v[80:81], s[38:39] op_sel_hi:[1,1,0]
	s_nop 0
	v_pk_mul_f32 v[80:81], v[94:95], v[80:81]
	s_nop 0
	v_pk_mul_f32 v[80:81], v[84:85], v[80:81]
	s_nop 0
	v_pk_mul_f32 v[84:85], v[82:83], v[80:81]
	v_pk_fma_f32 v[80:81], v[82:83], v[80:81], v[82:83] neg_lo:[1,0,0] neg_hi:[1,0,0]
	s_nop 0
	v_cndmask_b32_e32 v84, v80, v84, vcc
	v_cmp_gt_f32_e32 vcc, 0, v83
	v_cvt_pk_bf16_f32 v80, v98, v99
	s_nop 1
	v_cndmask_b32_e32 v83, v81, v85, vcc
	s_and_b64 vcc, exec, s[8:9]
	v_cvt_pk_bf16_f32 v81, v100, v101
	v_cvt_pk_bf16_f32 v82, v86, v87
	v_cvt_pk_bf16_f32 v83, v84, v83
	global_store_dwordx4 v[96:97], v[80:83], off offset:256
	s_cbranch_vccnz .LBB0_241
	v_lshlrev_b32_e32 v84, 16, v80
	v_and_b32_e32 v80, 0xffff0000, v80
	v_lshlrev_b32_e32 v86, 16, v81
	v_and_b32_e32 v88, 0xffff0000, v81
	v_lshlrev_b32_e32 v90, 16, v82
	v_and_b32_e32 v82, 0xffff0000, v82
	v_lshlrev_b32_e32 v94, 16, v83
	v_and_b32_e32 v96, 0xffff0000, v83
	v_mul_f32_e32 v85, v84, v84
	v_mul_f32_e32 v81, v80, v80
	v_mul_f32_e32 v87, v86, v86
	v_mul_f32_e32 v89, v88, v88
	v_mul_f32_e32 v91, v90, v90
	v_mul_f32_e32 v83, v82, v82
	v_mul_f32_e32 v95, v94, v94
	v_mul_f32_e32 v97, v96, v96
	v_pk_add_f32 v[80:81], v[84:85], v[80:81]
	v_pk_add_f32 v[84:85], v[86:87], v[88:89]
	v_pk_add_f32 v[82:83], v[90:91], v[82:83]
	v_pk_add_f32 v[80:81], v[80:81], v[84:85]
	v_pk_add_f32 v[84:85], v[94:95], v[96:97]
	s_nop 0
	v_pk_add_f32 v[82:83], v[82:83], v[84:85]
	s_nop 0
	v_pk_add_f32 v[80:81], v[80:81], v[82:83]
	s_nop 0
	v_pk_add_f32 v[80:81], v[92:93], v[80:81]
	s_nop 0
	v_mov_b32_e32 v82, v80
	v_mov_b32_e32 v83, v81
	s_nop 0
	v_permlane16_swap_b32_e32 v80, v82
	v_permlane16_swap_b32_e32 v81, v83
	v_pk_add_f32 v[80:81], v[80:81], v[82:83]
	s_nop 0
	v_mov_b32_e32 v82, v80
	v_mov_b32_e32 v83, v81
	s_nop 0
	v_permlane32_swap_b32_e32 v80, v82
	v_permlane32_swap_b32_e32 v81, v83
	v_pk_add_f32 v[80:81], v[80:81], v[82:83]
	s_and_saveexec_b64 s[10:11], s[4:5]
	s_cbranch_execz .LBB0_240
	v_lshlrev_b64 v[84:85], 8, v[160:161]
	v_lshl_add_u64 v[84:85], s[16:17], 0, v[84:85]
	v_lshl_add_u64 v[84:85], s[50:51], 2, v[84:85]
	global_store_dwordx2 v[84:85], v[80:81], off

.LBB0_241:
	s_nop 0
	s_nop 0
	v_permlane32_swap_b32_e32 v189, v190
	v_add_f32_e32 v80, v189, v190
	v_fmamk_f32 v80, v80, 0x3a800000, v177
	v_mov_b64_e32 v[86:87], s[30:31]
	s_waitcnt lgkmcnt(1)
	s_waitcnt lgkmcnt(0)
	v_rsq_f32_e32 v82, v80
	s_nop 0
	v_pk_mul_f32 v[76:77], v[76:77], v[82:83] op_sel_hi:[1,0]
	v_pk_mul_f32 v[78:79], v[78:79], v[82:83] op_sel_hi:[1,0]
	v_and_b32_e32 v85, 0x7fffffff, v77
	v_and_b32_e32 v84, 0x7fffffff, v76
	v_pk_fma_f32 v[84:85], v[84:85], s[26:27], 1.0 op_sel_hi:[1,0,0]
	v_pk_mul_f32 v[90:91], v[76:77], v[76:77]
	v_rcp_f32_e32 v84, v84
	v_rcp_f32_e32 v85, v85
	v_pk_mul_f32 v[90:91], v[90:91], s[40:41] op_sel_hi:[1,0]
	v_and_b32_e32 v93, 0x7fffffff, v79
	v_exp_f32_e32 v90, v90
	v_pk_fma_f32 v[88:89], v[84:85], s[28:29], v[86:87] op_sel_hi:[1,0,0]
	v_exp_f32_e32 v91, v91
	v_pk_fma_f32 v[88:89], v[84:85], v[88:89], s[34:35] op_sel_hi:[1,1,0]
	v_and_b32_e32 v92, 0x7fffffff, v78
	v_pk_fma_f32 v[88:89], v[84:85], v[88:89], s[36:37] op_sel_hi:[1,1,0]
	v_pk_fma_f32 v[92:93], v[92:93], s[26:27], 1.0 op_sel_hi:[1,0,0]
	v_pk_fma_f32 v[88:89], v[84:85], v[88:89], s[38:39] op_sel_hi:[1,1,0]
	v_rcp_f32_e32 v92, v92
	v_pk_mul_f32 v[84:85], v[84:85], v[88:89]
	v_rcp_f32_e32 v93, v93
	v_pk_mul_f32 v[84:85], v[90:91], v[84:85]
	v_cmp_gt_f32_e32 vcc, 0, v76
	v_pk_mul_f32 v[90:91], v[76:77], v[84:85]
	v_pk_fma_f32 v[84:85], v[76:77], v[84:85], v[76:77] neg_lo:[1,0,0] neg_hi:[1,0,0]
	v_pk_mul_f32 v[74:75], v[74:75], v[82:83] op_sel_hi:[1,0]
	v_pk_mul_f32 v[72:73], v[72:73], v[82:83] op_sel_hi:[1,0]
	v_pk_mul_f32 v[88:89], v[78:79], v[78:79]
	v_cndmask_b32_e32 v83, v84, v90, vcc
	v_cmp_gt_f32_e32 vcc, 0, v77
	v_pk_fma_f32 v[76:77], v[92:93], s[28:29], v[86:87] op_sel_hi:[1,0,0]
	v_lshlrev_b64 v[80:81], 12, v[158:159]
	v_cndmask_b32_e32 v90, v85, v91, vcc
	v_pk_mul_f32 v[84:85], v[88:89], s[40:41] op_sel_hi:[1,0]
	v_pk_fma_f32 v[76:77], v[92:93], v[76:77], s[34:35] op_sel_hi:[1,1,0]
	v_exp_f32_e32 v84, v84
	v_exp_f32_e32 v85, v85
	v_pk_fma_f32 v[76:77], v[92:93], v[76:77], s[36:37] op_sel_hi:[1,1,0]
	v_and_b32_e32 v89, 0x7fffffff, v73
	v_and_b32_e32 v88, 0x7fffffff, v72
	v_pk_fma_f32 v[76:77], v[92:93], v[76:77], s[38:39] op_sel_hi:[1,1,0]
	v_pk_fma_f32 v[88:89], v[88:89], s[26:27], 1.0 op_sel_hi:[1,0,0]
	v_pk_mul_f32 v[76:77], v[92:93], v[76:77]
	v_rcp_f32_e32 v88, v88
	v_rcp_f32_e32 v89, v89
	v_pk_mul_f32 v[76:77], v[84:85], v[76:77]
	v_max_f32_e32 v91, 0, v78
	v_max_f32_e32 v92, 0, v79
	v_fma_f32 v91, -|v78|, v76, v91
	v_fma_f32 v92, -|v79|, v77, v92
	v_lshl_add_u64 v[80:81], v[152:153], 0, v[80:81]
	v_pk_mul_f32 v[78:79], v[72:73], v[72:73]
	s_nop 0
	v_pk_fma_f32 v[76:77], v[88:89], s[28:29], v[86:87] op_sel_hi:[1,0,0]
	v_pk_mul_f32 v[78:79], v[78:79], s[40:41] op_sel_hi:[1,0]
	v_pk_fma_f32 v[76:77], v[88:89], v[76:77], s[34:35] op_sel_hi:[1,1,0]
	v_exp_f32_e32 v78, v78
	v_pk_fma_f32 v[76:77], v[88:89], v[76:77], s[36:37] op_sel_hi:[1,1,0]
	v_exp_f32_e32 v79, v79
	v_pk_fma_f32 v[76:77], v[88:89], v[76:77], s[38:39] op_sel_hi:[1,1,0]
	v_pk_mul_f32 v[76:77], v[88:89], v[76:77]
	v_and_b32_e32 v89, 0x7fffffff, v75
	v_and_b32_e32 v88, 0x7fffffff, v74
	v_pk_fma_f32 v[88:89], v[88:89], s[26:27], 1.0 op_sel_hi:[1,0,0]
	v_pk_mul_f32 v[76:77], v[78:79], v[76:77]
	v_rcp_f32_e32 v88, v88
	v_rcp_f32_e32 v89, v89
	v_max_f32_e32 v78, 0, v72
	v_max_f32_e32 v79, 0, v73
	v_fma_f32 v78, -|v72|, v76, v78
	v_fma_f32 v79, -|v73|, v77, v79
	v_pk_mul_f32 v[84:85], v[74:75], v[74:75]
	v_pk_fma_f32 v[72:73], v[88:89], s[28:29], v[86:87] op_sel_hi:[1,0,0]
	s_nop 0
	v_pk_mul_f32 v[76:77], v[84:85], s[40:41] op_sel_hi:[1,0]
	v_pk_fma_f32 v[72:73], v[88:89], v[72:73], s[34:35] op_sel_hi:[1,1,0]
	v_exp_f32_e32 v76, v76
	v_exp_f32_e32 v77, v77
	v_pk_fma_f32 v[72:73], v[88:89], v[72:73], s[36:37] op_sel_hi:[1,1,0]
	v_cmp_gt_f32_e32 vcc, 0, v74
	v_pk_fma_f32 v[72:73], v[88:89], v[72:73], s[38:39] op_sel_hi:[1,1,0]
	s_nop 0
	v_pk_mul_f32 v[72:73], v[88:89], v[72:73]
	s_nop 0
	v_pk_mul_f32 v[72:73], v[76:77], v[72:73]
	s_nop 0
	v_pk_mul_f32 v[76:77], v[74:75], v[72:73]
	v_pk_fma_f32 v[72:73], v[74:75], v[72:73], v[74:75] neg_lo:[1,0,0] neg_hi:[1,0,0]
	s_nop 0
	v_cndmask_b32_e32 v76, v72, v76, vcc
	v_cmp_gt_f32_e32 vcc, 0, v75
	v_cvt_pk_bf16_f32 v72, v83, v90
	s_nop 1
	v_cndmask_b32_e32 v75, v73, v77, vcc
	v_cvt_pk_bf16_f32 v73, v91, v92
	v_cvt_pk_bf16_f32 v74, v78, v79
	v_cvt_pk_bf16_f32 v75, v76, v75
	v_mov_b32_e32 v76, 0
	s_and_b64 vcc, exec, s[8:9]
	v_mov_b32_e32 v77, 0
	global_store_dwordx4 v[80:81], v[72:75], off
	s_cbranch_vccnz .LBB0_243
	v_and_b32_e32 v77, 16, v72
	v_and_b32_e32 v76, 0xffff0000, v72
	v_lshlrev_b32_e32 v85, 16, v73
	v_lshlrev_b32_e32 v84, 16, v74
	v_and_b32_e32 v78, 0xffff0000, v73
	v_mov_b32_e32 v79, v76
	v_pk_mov_b32 v[90:91], v[84:85], v[76:77] op_sel:[1,0]
	v_lshlrev_b32_e32 v72, 16, v72
	v_and_b32_e32 v86, 0xffff0000, v75
	v_mov_b32_e32 v87, v78
	v_and_b32_e32 v74, 0xffff0000, v74
	v_lshlrev_b32_e32 v88, 16, v75
	v_mov_b32_e32 v75, v85
	v_mov_b32_e32 v73, v78
	v_mov_b32_e32 v89, v78
	v_pk_add_f32 v[92:93], v[78:79], v[90:91]
	v_pk_mul_f32 v[78:79], v[78:79], v[90:91]
	v_pk_add_f32 v[76:77], v[72:73], v[76:77] op_sel_hi:[0,1]
	v_mov_b32_e32 v93, v79
	v_pk_add_f32 v[78:79], v[84:85], v[74:75]
	v_pk_mul_f32 v[90:91], v[84:85], v[84:85]
	v_mov_b32_e32 v75, v86
	v_mul_f32_e32 v77, v72, v72
	v_mov_b32_e32 v79, v91
	v_pk_add_f32 v[90:91], v[86:87], v[88:89]
	v_pk_mul_f32 v[72:73], v[86:87], v[72:73]
	v_mov_b32_e32 v85, v88
	v_pk_mul_f32 v[74:75], v[74:75], v[74:75]
	v_mov_b32_e32 v91, v73
	v_pk_fma_f32 v[74:75], v[84:85], v[84:85], v[74:75]
	v_pk_add_f32 v[76:77], v[76:77], v[92:93]
	v_pk_add_f32 v[72:73], v[78:79], v[90:91]
	v_pk_add_f32 v[74:75], v[74:75], v[74:75] op_sel_hi:[0,1]
	v_pk_add_f32 v[72:73], v[76:77], v[72:73]
	v_mov_b32_e32 v137, v75
	v_pk_add_f32 v[76:77], v[72:73], v[136:137]
.LBB0_243:
	v_mov_b32_e32 v83, v82
	v_pk_mul_f32 v[68:69], v[68:69], v[82:83]
	v_mov_b32_e32 v72, v82
	v_and_b32_e32 v75, 0x7fffffff, v69
	v_and_b32_e32 v74, 0x7fffffff, v68
	v_pk_fma_f32 v[74:75], v[74:75], s[26:27], 1.0 op_sel_hi:[1,0,0]
	v_mov_b32_e32 v73, v82
	v_rcp_f32_e32 v74, v74
	v_rcp_f32_e32 v75, v75
	v_pk_mul_f32 v[70:71], v[70:71], v[72:73]
	v_pk_mul_f32 v[66:67], v[66:67], v[72:73]
	v_pk_mul_f32 v[64:65], v[64:65], v[82:83]
	v_mov_b64_e32 v[72:73], s[30:31]
	v_pk_mul_f32 v[82:83], v[68:69], v[68:69]
	v_pk_fma_f32 v[78:79], v[74:75], s[28:29], v[72:73] op_sel_hi:[1,0,0]
	v_pk_mul_f32 v[82:83], v[82:83], s[40:41] op_sel_hi:[1,0]
	v_pk_fma_f32 v[78:79], v[74:75], v[78:79], s[34:35] op_sel_hi:[1,1,0]
	v_exp_f32_e32 v82, v82
	v_exp_f32_e32 v83, v83
	v_pk_fma_f32 v[78:79], v[74:75], v[78:79], s[36:37] op_sel_hi:[1,1,0]
	v_and_b32_e32 v85, 0x7fffffff, v71
	v_and_b32_e32 v84, 0x7fffffff, v70
	v_pk_fma_f32 v[78:79], v[74:75], v[78:79], s[38:39] op_sel_hi:[1,1,0]
	v_pk_fma_f32 v[84:85], v[84:85], s[26:27], 1.0 op_sel_hi:[1,0,0]
	v_pk_mul_f32 v[74:75], v[74:75], v[78:79]
	v_rcp_f32_e32 v84, v84
	v_rcp_f32_e32 v85, v85
	v_pk_mul_f32 v[74:75], v[82:83], v[74:75]
	v_max_f32_e32 v82, 0, v68
	v_max_f32_e32 v83, 0, v69
	v_fma_f32 v82, -|v68|, v74, v82
	v_fma_f32 v83, -|v69|, v75, v83
	v_pk_mul_f32 v[78:79], v[70:71], v[70:71]
	v_pk_fma_f32 v[68:69], v[84:85], s[28:29], v[72:73] op_sel_hi:[1,0,0]
	s_nop 0
	v_pk_mul_f32 v[74:75], v[78:79], s[40:41] op_sel_hi:[1,0]
	v_pk_fma_f32 v[68:69], v[84:85], v[68:69], s[34:35] op_sel_hi:[1,1,0]
	v_exp_f32_e32 v74, v74
	v_exp_f32_e32 v75, v75
	v_pk_fma_f32 v[68:69], v[84:85], v[68:69], s[36:37] op_sel_hi:[1,1,0]
	v_and_b32_e32 v79, 0x7fffffff, v65
	v_and_b32_e32 v78, 0x7fffffff, v64
	v_pk_fma_f32 v[68:69], v[84:85], v[68:69], s[38:39] op_sel_hi:[1,1,0]
	v_pk_fma_f32 v[78:79], v[78:79], s[26:27], 1.0 op_sel_hi:[1,0,0]
	v_pk_mul_f32 v[68:69], v[84:85], v[68:69]
	v_rcp_f32_e32 v78, v78
	v_rcp_f32_e32 v79, v79
	v_pk_mul_f32 v[68:69], v[74:75], v[68:69]
	v_max_f32_e32 v84, 0, v70
	v_max_f32_e32 v85, 0, v71
	v_fma_f32 v84, -|v70|, v68, v84
	v_fma_f32 v85, -|v71|, v69, v85
	s_nop 0
	v_pk_mul_f32 v[70:71], v[64:65], v[64:65]
	s_nop 0
	v_pk_fma_f32 v[68:69], v[78:79], s[28:29], v[72:73] op_sel_hi:[1,0,0]
	v_pk_mul_f32 v[70:71], v[70:71], s[40:41] op_sel_hi:[1,0]
	v_pk_fma_f32 v[68:69], v[78:79], v[68:69], s[34:35] op_sel_hi:[1,1,0]
	v_exp_f32_e32 v70, v70
	v_pk_fma_f32 v[68:69], v[78:79], v[68:69], s[36:37] op_sel_hi:[1,1,0]
	v_exp_f32_e32 v71, v71
	v_pk_fma_f32 v[68:69], v[78:79], v[68:69], s[38:39] op_sel_hi:[1,1,0]
	v_pk_mul_f32 v[68:69], v[78:79], v[68:69]
	v_and_b32_e32 v79, 0x7fffffff, v67
	v_and_b32_e32 v78, 0x7fffffff, v66
	v_pk_fma_f32 v[78:79], v[78:79], s[26:27], 1.0 op_sel_hi:[1,0,0]
	v_pk_mul_f32 v[68:69], v[70:71], v[68:69]
	v_rcp_f32_e32 v78, v78
	v_rcp_f32_e32 v79, v79
	v_max_f32_e32 v70, 0, v64
	v_max_f32_e32 v71, 0, v65
	v_fma_f32 v70, -|v64|, v68, v70
	v_fma_f32 v71, -|v65|, v69, v71
	v_pk_mul_f32 v[74:75], v[66:67], v[66:67]
	v_pk_fma_f32 v[64:65], v[78:79], s[28:29], v[72:73] op_sel_hi:[1,0,0]
	s_nop 0
	v_pk_mul_f32 v[68:69], v[74:75], s[40:41] op_sel_hi:[1,0]
	v_pk_fma_f32 v[64:65], v[78:79], v[64:65], s[34:35] op_sel_hi:[1,1,0]
	v_exp_f32_e32 v68, v68
	v_exp_f32_e32 v69, v69
	v_pk_fma_f32 v[64:65], v[78:79], v[64:65], s[36:37] op_sel_hi:[1,1,0]
	v_cmp_gt_f32_e32 vcc, 0, v66
	v_pk_fma_f32 v[64:65], v[78:79], v[64:65], s[38:39] op_sel_hi:[1,1,0]
	s_nop 0
	v_pk_mul_f32 v[64:65], v[78:79], v[64:65]
	s_nop 0
	v_pk_mul_f32 v[64:65], v[68:69], v[64:65]
	s_nop 0
	v_pk_mul_f32 v[68:69], v[66:67], v[64:65]
	v_pk_fma_f32 v[64:65], v[66:67], v[64:65], v[66:67] neg_lo:[1,0,0] neg_hi:[1,0,0]
	s_nop 0
	v_cndmask_b32_e32 v68, v64, v68, vcc
	v_cmp_gt_f32_e32 vcc, 0, v67
	v_cvt_pk_bf16_f32 v64, v82, v83
	s_nop 1
	v_cndmask_b32_e32 v67, v65, v69, vcc
	s_and_b64 vcc, exec, s[8:9]
	v_cvt_pk_bf16_f32 v65, v84, v85
	v_cvt_pk_bf16_f32 v66, v70, v71
	v_cvt_pk_bf16_f32 v67, v68, v67
	global_store_dwordx4 v[80:81], v[64:67], off offset:256
	s_cbranch_vccnz .LBB0_247
	v_lshlrev_b32_e32 v68, 16, v64
	v_and_b32_e32 v64, 0xffff0000, v64
	v_lshlrev_b32_e32 v70, 16, v65
	v_and_b32_e32 v72, 0xffff0000, v65
	v_lshlrev_b32_e32 v74, 16, v66
	v_and_b32_e32 v66, 0xffff0000, v66
	v_lshlrev_b32_e32 v78, 16, v67
	v_and_b32_e32 v80, 0xffff0000, v67
	v_mul_f32_e32 v69, v68, v68
	v_mul_f32_e32 v65, v64, v64
	v_mul_f32_e32 v71, v70, v70
	v_mul_f32_e32 v73, v72, v72
	v_mul_f32_e32 v75, v74, v74
	v_mul_f32_e32 v67, v66, v66
	v_mul_f32_e32 v79, v78, v78
	v_mul_f32_e32 v81, v80, v80
	v_pk_add_f32 v[64:65], v[68:69], v[64:65]
	v_pk_add_f32 v[68:69], v[70:71], v[72:73]
	v_pk_add_f32 v[66:67], v[74:75], v[66:67]
	v_pk_add_f32 v[64:65], v[64:65], v[68:69]
	v_pk_add_f32 v[68:69], v[78:79], v[80:81]
	s_nop 0
	v_pk_add_f32 v[66:67], v[66:67], v[68:69]
	s_nop 0
	v_pk_add_f32 v[64:65], v[64:65], v[66:67]
	s_nop 0
	v_pk_add_f32 v[64:65], v[76:77], v[64:65]
	s_nop 0
	v_mov_b32_e32 v66, v64
	v_mov_b32_e32 v67, v65
	s_nop 0
	v_permlane16_swap_b32_e32 v64, v66
	v_permlane16_swap_b32_e32 v65, v67
	v_pk_add_f32 v[64:65], v[64:65], v[66:67]
	s_nop 0
	v_mov_b32_e32 v66, v64
	v_mov_b32_e32 v67, v65
	s_nop 0
	v_permlane32_swap_b32_e32 v64, v66
	v_permlane32_swap_b32_e32 v65, v67
	v_pk_add_f32 v[64:65], v[64:65], v[66:67]
	s_and_saveexec_b64 s[10:11], s[4:5]
	s_cbranch_execz .LBB0_246
	v_lshlrev_b64 v[68:69], 8, v[158:159]
	v_lshl_add_u64 v[68:69], s[16:17], 0, v[68:69]
	v_lshl_add_u64 v[68:69], s[50:51], 2, v[68:69]
	global_store_dwordx2 v[68:69], v[64:65], off

.LBB0_247:
	s_nop 0
	s_nop 0
	v_permlane32_swap_b32_e32 v187, v188
	v_add_f32_e32 v64, v187, v188
	v_fmamk_f32 v64, v64, 0x3a800000, v177
	v_mov_b64_e32 v[70:71], s[30:31]
	s_waitcnt lgkmcnt(1)
	s_waitcnt lgkmcnt(0)
	v_rsq_f32_e32 v66, v64
	s_nop 0
	v_pk_mul_f32 v[60:61], v[60:61], v[66:67] op_sel_hi:[1,0]
	v_pk_mul_f32 v[62:63], v[62:63], v[66:67] op_sel_hi:[1,0]
	v_and_b32_e32 v69, 0x7fffffff, v61
	v_and_b32_e32 v68, 0x7fffffff, v60
	v_pk_fma_f32 v[68:69], v[68:69], s[26:27], 1.0 op_sel_hi:[1,0,0]
	v_pk_mul_f32 v[74:75], v[60:61], v[60:61]
	v_rcp_f32_e32 v68, v68
	v_rcp_f32_e32 v69, v69
	v_pk_mul_f32 v[74:75], v[74:75], s[40:41] op_sel_hi:[1,0]
	v_and_b32_e32 v77, 0x7fffffff, v63
	v_exp_f32_e32 v74, v74
	v_pk_fma_f32 v[72:73], v[68:69], s[28:29], v[70:71] op_sel_hi:[1,0,0]
	v_exp_f32_e32 v75, v75
	v_pk_fma_f32 v[72:73], v[68:69], v[72:73], s[34:35] op_sel_hi:[1,1,0]
	v_and_b32_e32 v76, 0x7fffffff, v62
	v_pk_fma_f32 v[72:73], v[68:69], v[72:73], s[36:37] op_sel_hi:[1,1,0]
	v_pk_fma_f32 v[76:77], v[76:77], s[26:27], 1.0 op_sel_hi:[1,0,0]
	v_pk_fma_f32 v[72:73], v[68:69], v[72:73], s[38:39] op_sel_hi:[1,1,0]
	v_rcp_f32_e32 v76, v76
	v_pk_mul_f32 v[68:69], v[68:69], v[72:73]
	v_rcp_f32_e32 v77, v77
	v_pk_mul_f32 v[68:69], v[74:75], v[68:69]
	v_cmp_gt_f32_e32 vcc, 0, v60
	v_pk_mul_f32 v[74:75], v[60:61], v[68:69]
	v_pk_fma_f32 v[68:69], v[60:61], v[68:69], v[60:61] neg_lo:[1,0,0] neg_hi:[1,0,0]
	v_pk_mul_f32 v[58:59], v[58:59], v[66:67] op_sel_hi:[1,0]
	v_pk_mul_f32 v[56:57], v[56:57], v[66:67] op_sel_hi:[1,0]
	v_pk_mul_f32 v[72:73], v[62:63], v[62:63]
	v_cndmask_b32_e32 v67, v68, v74, vcc
	v_cmp_gt_f32_e32 vcc, 0, v61
	v_pk_fma_f32 v[60:61], v[76:77], s[28:29], v[70:71] op_sel_hi:[1,0,0]
	v_lshlrev_b64 v[64:65], 12, v[156:157]
	v_cndmask_b32_e32 v74, v69, v75, vcc
	v_pk_mul_f32 v[68:69], v[72:73], s[40:41] op_sel_hi:[1,0]
	v_pk_fma_f32 v[60:61], v[76:77], v[60:61], s[34:35] op_sel_hi:[1,1,0]
	v_exp_f32_e32 v68, v68
	v_exp_f32_e32 v69, v69
	v_pk_fma_f32 v[60:61], v[76:77], v[60:61], s[36:37] op_sel_hi:[1,1,0]
	v_and_b32_e32 v73, 0x7fffffff, v57
	v_and_b32_e32 v72, 0x7fffffff, v56
	v_pk_fma_f32 v[60:61], v[76:77], v[60:61], s[38:39] op_sel_hi:[1,1,0]
	v_pk_fma_f32 v[72:73], v[72:73], s[26:27], 1.0 op_sel_hi:[1,0,0]
	v_pk_mul_f32 v[60:61], v[76:77], v[60:61]
	v_rcp_f32_e32 v72, v72
	v_rcp_f32_e32 v73, v73
	v_pk_mul_f32 v[60:61], v[68:69], v[60:61]
	v_max_f32_e32 v75, 0, v62
	v_max_f32_e32 v76, 0, v63
	v_fma_f32 v75, -|v62|, v60, v75
	v_fma_f32 v76, -|v63|, v61, v76
	v_lshl_add_u64 v[64:65], v[152:153], 0, v[64:65]
	v_pk_mul_f32 v[62:63], v[56:57], v[56:57]
	s_nop 0
	v_pk_fma_f32 v[60:61], v[72:73], s[28:29], v[70:71] op_sel_hi:[1,0,0]
	v_pk_mul_f32 v[62:63], v[62:63], s[40:41] op_sel_hi:[1,0]
	v_pk_fma_f32 v[60:61], v[72:73], v[60:61], s[34:35] op_sel_hi:[1,1,0]
	v_exp_f32_e32 v62, v62
	v_pk_fma_f32 v[60:61], v[72:73], v[60:61], s[36:37] op_sel_hi:[1,1,0]
	v_exp_f32_e32 v63, v63
	v_pk_fma_f32 v[60:61], v[72:73], v[60:61], s[38:39] op_sel_hi:[1,1,0]
	v_pk_mul_f32 v[60:61], v[72:73], v[60:61]
	v_and_b32_e32 v73, 0x7fffffff, v59
	v_and_b32_e32 v72, 0x7fffffff, v58
	v_pk_fma_f32 v[72:73], v[72:73], s[26:27], 1.0 op_sel_hi:[1,0,0]
	v_pk_mul_f32 v[60:61], v[62:63], v[60:61]
	v_rcp_f32_e32 v72, v72
	v_rcp_f32_e32 v73, v73
	v_max_f32_e32 v62, 0, v56
	v_max_f32_e32 v63, 0, v57
	v_fma_f32 v62, -|v56|, v60, v62
	v_fma_f32 v63, -|v57|, v61, v63
	v_pk_mul_f32 v[68:69], v[58:59], v[58:59]
	v_pk_fma_f32 v[56:57], v[72:73], s[28:29], v[70:71] op_sel_hi:[1,0,0]
	s_nop 0
	v_pk_mul_f32 v[60:61], v[68:69], s[40:41] op_sel_hi:[1,0]
	v_pk_fma_f32 v[56:57], v[72:73], v[56:57], s[34:35] op_sel_hi:[1,1,0]
	v_exp_f32_e32 v60, v60
	v_exp_f32_e32 v61, v61
	v_pk_fma_f32 v[56:57], v[72:73], v[56:57], s[36:37] op_sel_hi:[1,1,0]
	v_cmp_gt_f32_e32 vcc, 0, v58
	v_pk_fma_f32 v[56:57], v[72:73], v[56:57], s[38:39] op_sel_hi:[1,1,0]
	s_nop 0
	v_pk_mul_f32 v[56:57], v[72:73], v[56:57]
	s_nop 0
	v_pk_mul_f32 v[56:57], v[60:61], v[56:57]
	s_nop 0
	v_pk_mul_f32 v[60:61], v[58:59], v[56:57]
	v_pk_fma_f32 v[56:57], v[58:59], v[56:57], v[58:59] neg_lo:[1,0,0] neg_hi:[1,0,0]
	s_nop 0
	v_cndmask_b32_e32 v60, v56, v60, vcc
	v_cmp_gt_f32_e32 vcc, 0, v59
	v_cvt_pk_bf16_f32 v56, v67, v74
	s_nop 1
	v_cndmask_b32_e32 v59, v57, v61, vcc
	v_cvt_pk_bf16_f32 v57, v75, v76
	v_cvt_pk_bf16_f32 v58, v62, v63
	v_cvt_pk_bf16_f32 v59, v60, v59
	v_mov_b32_e32 v60, 0
	s_and_b64 vcc, exec, s[8:9]
	v_mov_b32_e32 v61, 0
	global_store_dwordx4 v[64:65], v[56:59], off
	s_cbranch_vccnz .LBB0_249
	v_and_b32_e32 v61, 16, v56
	v_and_b32_e32 v60, 0xffff0000, v56
	v_lshlrev_b32_e32 v69, 16, v57
	v_lshlrev_b32_e32 v68, 16, v58
	v_and_b32_e32 v62, 0xffff0000, v57
	v_mov_b32_e32 v63, v60
	v_pk_mov_b32 v[74:75], v[68:69], v[60:61] op_sel:[1,0]
	v_lshlrev_b32_e32 v56, 16, v56
	v_and_b32_e32 v70, 0xffff0000, v59
	v_mov_b32_e32 v71, v62
	v_and_b32_e32 v58, 0xffff0000, v58
	v_lshlrev_b32_e32 v72, 16, v59
	v_mov_b32_e32 v59, v69
	v_mov_b32_e32 v57, v62
	v_mov_b32_e32 v73, v62
	v_pk_add_f32 v[76:77], v[62:63], v[74:75]
	v_pk_mul_f32 v[62:63], v[62:63], v[74:75]
	v_pk_add_f32 v[60:61], v[56:57], v[60:61] op_sel_hi:[0,1]
	v_mov_b32_e32 v77, v63
	v_pk_add_f32 v[62:63], v[68:69], v[58:59]
	v_pk_mul_f32 v[74:75], v[68:69], v[68:69]
	v_mov_b32_e32 v59, v70
	v_mul_f32_e32 v61, v56, v56
	v_mov_b32_e32 v63, v75
	v_pk_add_f32 v[74:75], v[70:71], v[72:73]
	v_pk_mul_f32 v[56:57], v[70:71], v[56:57]
	v_mov_b32_e32 v69, v72
	v_pk_mul_f32 v[58:59], v[58:59], v[58:59]
	v_mov_b32_e32 v75, v57
	v_pk_fma_f32 v[58:59], v[68:69], v[68:69], v[58:59]
	v_pk_add_f32 v[60:61], v[60:61], v[76:77]
	v_pk_add_f32 v[56:57], v[62:63], v[74:75]
	v_pk_add_f32 v[58:59], v[58:59], v[58:59] op_sel_hi:[0,1]
	v_pk_add_f32 v[56:57], v[60:61], v[56:57]
	v_mov_b32_e32 v137, v59
	v_pk_add_f32 v[60:61], v[56:57], v[136:137]
.LBB0_249:
	v_mov_b32_e32 v67, v66
	v_pk_mul_f32 v[52:53], v[52:53], v[66:67]
	v_mov_b32_e32 v56, v66
	v_and_b32_e32 v59, 0x7fffffff, v53
	v_and_b32_e32 v58, 0x7fffffff, v52
	v_pk_fma_f32 v[58:59], v[58:59], s[26:27], 1.0 op_sel_hi:[1,0,0]
	v_mov_b32_e32 v57, v66
	v_rcp_f32_e32 v58, v58
	v_rcp_f32_e32 v59, v59
	v_pk_mul_f32 v[54:55], v[54:55], v[56:57]
	v_pk_mul_f32 v[50:51], v[50:51], v[56:57]
	v_pk_mul_f32 v[48:49], v[48:49], v[66:67]
	v_mov_b64_e32 v[56:57], s[30:31]
	v_pk_mul_f32 v[66:67], v[52:53], v[52:53]
	v_pk_fma_f32 v[62:63], v[58:59], s[28:29], v[56:57] op_sel_hi:[1,0,0]
	v_pk_mul_f32 v[66:67], v[66:67], s[40:41] op_sel_hi:[1,0]
	v_pk_fma_f32 v[62:63], v[58:59], v[62:63], s[34:35] op_sel_hi:[1,1,0]
	v_exp_f32_e32 v66, v66
	v_exp_f32_e32 v67, v67
	v_pk_fma_f32 v[62:63], v[58:59], v[62:63], s[36:37] op_sel_hi:[1,1,0]
	v_and_b32_e32 v69, 0x7fffffff, v55
	v_and_b32_e32 v68, 0x7fffffff, v54
	v_pk_fma_f32 v[62:63], v[58:59], v[62:63], s[38:39] op_sel_hi:[1,1,0]
	v_pk_fma_f32 v[68:69], v[68:69], s[26:27], 1.0 op_sel_hi:[1,0,0]
	v_pk_mul_f32 v[58:59], v[58:59], v[62:63]
	v_rcp_f32_e32 v68, v68
	v_rcp_f32_e32 v69, v69
	v_pk_mul_f32 v[58:59], v[66:67], v[58:59]
	v_max_f32_e32 v66, 0, v52
	v_max_f32_e32 v67, 0, v53
	v_fma_f32 v66, -|v52|, v58, v66
	v_fma_f32 v67, -|v53|, v59, v67
	v_pk_mul_f32 v[62:63], v[54:55], v[54:55]
	v_pk_fma_f32 v[52:53], v[68:69], s[28:29], v[56:57] op_sel_hi:[1,0,0]
	s_nop 0
	v_pk_mul_f32 v[58:59], v[62:63], s[40:41] op_sel_hi:[1,0]
	v_pk_fma_f32 v[52:53], v[68:69], v[52:53], s[34:35] op_sel_hi:[1,1,0]
	v_exp_f32_e32 v58, v58
	v_exp_f32_e32 v59, v59
	v_pk_fma_f32 v[52:53], v[68:69], v[52:53], s[36:37] op_sel_hi:[1,1,0]
	v_and_b32_e32 v63, 0x7fffffff, v49
	v_and_b32_e32 v62, 0x7fffffff, v48
	v_pk_fma_f32 v[52:53], v[68:69], v[52:53], s[38:39] op_sel_hi:[1,1,0]
	v_pk_fma_f32 v[62:63], v[62:63], s[26:27], 1.0 op_sel_hi:[1,0,0]
	v_pk_mul_f32 v[52:53], v[68:69], v[52:53]
	v_rcp_f32_e32 v62, v62
	v_rcp_f32_e32 v63, v63
	v_pk_mul_f32 v[52:53], v[58:59], v[52:53]
	v_max_f32_e32 v68, 0, v54
	v_max_f32_e32 v69, 0, v55
	v_fma_f32 v68, -|v54|, v52, v68
	v_fma_f32 v69, -|v55|, v53, v69
	s_nop 0
	v_pk_mul_f32 v[54:55], v[48:49], v[48:49]
	s_nop 0
	v_pk_fma_f32 v[52:53], v[62:63], s[28:29], v[56:57] op_sel_hi:[1,0,0]
	v_pk_mul_f32 v[54:55], v[54:55], s[40:41] op_sel_hi:[1,0]
	v_pk_fma_f32 v[52:53], v[62:63], v[52:53], s[34:35] op_sel_hi:[1,1,0]
	v_exp_f32_e32 v54, v54
	v_pk_fma_f32 v[52:53], v[62:63], v[52:53], s[36:37] op_sel_hi:[1,1,0]
	v_exp_f32_e32 v55, v55
	v_pk_fma_f32 v[52:53], v[62:63], v[52:53], s[38:39] op_sel_hi:[1,1,0]
	v_pk_mul_f32 v[52:53], v[62:63], v[52:53]
	v_and_b32_e32 v63, 0x7fffffff, v51
	v_and_b32_e32 v62, 0x7fffffff, v50
	v_pk_fma_f32 v[62:63], v[62:63], s[26:27], 1.0 op_sel_hi:[1,0,0]
	v_pk_mul_f32 v[52:53], v[54:55], v[52:53]
	v_rcp_f32_e32 v62, v62
	v_rcp_f32_e32 v63, v63
	v_max_f32_e32 v54, 0, v48
	v_max_f32_e32 v55, 0, v49
	v_fma_f32 v54, -|v48|, v52, v54
	v_fma_f32 v55, -|v49|, v53, v55
	v_pk_mul_f32 v[58:59], v[50:51], v[50:51]
	v_pk_fma_f32 v[48:49], v[62:63], s[28:29], v[56:57] op_sel_hi:[1,0,0]
	s_nop 0
	v_pk_mul_f32 v[52:53], v[58:59], s[40:41] op_sel_hi:[1,0]
	v_pk_fma_f32 v[48:49], v[62:63], v[48:49], s[34:35] op_sel_hi:[1,1,0]
	v_exp_f32_e32 v52, v52
	v_exp_f32_e32 v53, v53
	v_pk_fma_f32 v[48:49], v[62:63], v[48:49], s[36:37] op_sel_hi:[1,1,0]
	v_cmp_gt_f32_e32 vcc, 0, v50
	v_pk_fma_f32 v[48:49], v[62:63], v[48:49], s[38:39] op_sel_hi:[1,1,0]
	s_nop 0
	v_pk_mul_f32 v[48:49], v[62:63], v[48:49]
	s_nop 0
	v_pk_mul_f32 v[48:49], v[52:53], v[48:49]
	s_nop 0
	v_pk_mul_f32 v[52:53], v[50:51], v[48:49]
	v_pk_fma_f32 v[48:49], v[50:51], v[48:49], v[50:51] neg_lo:[1,0,0] neg_hi:[1,0,0]
	s_nop 0
	v_cndmask_b32_e32 v52, v48, v52, vcc
	v_cmp_gt_f32_e32 vcc, 0, v51
	v_cvt_pk_bf16_f32 v48, v66, v67
	s_nop 1
	v_cndmask_b32_e32 v51, v49, v53, vcc
	s_and_b64 vcc, exec, s[8:9]
	v_cvt_pk_bf16_f32 v49, v68, v69
	v_cvt_pk_bf16_f32 v50, v54, v55
	v_cvt_pk_bf16_f32 v51, v52, v51
	global_store_dwordx4 v[64:65], v[48:51], off offset:256
	s_cbranch_vccnz .LBB0_253
	v_lshlrev_b32_e32 v52, 16, v48
	v_and_b32_e32 v48, 0xffff0000, v48
	v_lshlrev_b32_e32 v54, 16, v49
	v_and_b32_e32 v56, 0xffff0000, v49
	v_lshlrev_b32_e32 v58, 16, v50
	v_and_b32_e32 v50, 0xffff0000, v50
	v_lshlrev_b32_e32 v62, 16, v51
	v_and_b32_e32 v64, 0xffff0000, v51
	v_mul_f32_e32 v53, v52, v52
	v_mul_f32_e32 v49, v48, v48
	v_mul_f32_e32 v55, v54, v54
	v_mul_f32_e32 v57, v56, v56
	v_mul_f32_e32 v59, v58, v58
	v_mul_f32_e32 v51, v50, v50
	v_mul_f32_e32 v63, v62, v62
	v_mul_f32_e32 v65, v64, v64
	v_pk_add_f32 v[48:49], v[52:53], v[48:49]
	v_pk_add_f32 v[52:53], v[54:55], v[56:57]
	v_pk_add_f32 v[50:51], v[58:59], v[50:51]
	v_pk_add_f32 v[48:49], v[48:49], v[52:53]
	v_pk_add_f32 v[52:53], v[62:63], v[64:65]
	s_nop 0
	v_pk_add_f32 v[50:51], v[50:51], v[52:53]
	s_nop 0
	v_pk_add_f32 v[48:49], v[48:49], v[50:51]
	s_nop 0
	v_pk_add_f32 v[48:49], v[60:61], v[48:49]
	s_nop 0
	v_mov_b32_e32 v50, v48
	v_mov_b32_e32 v51, v49
	s_nop 0
	v_permlane16_swap_b32_e32 v48, v50
	v_permlane16_swap_b32_e32 v49, v51
	v_pk_add_f32 v[48:49], v[48:49], v[50:51]
	s_nop 0
	v_mov_b32_e32 v50, v48
	v_mov_b32_e32 v51, v49
	s_nop 0
	v_permlane32_swap_b32_e32 v48, v50
	v_permlane32_swap_b32_e32 v49, v51
	v_pk_add_f32 v[48:49], v[48:49], v[50:51]
	s_and_saveexec_b64 s[10:11], s[4:5]
	s_cbranch_execz .LBB0_252
	v_lshlrev_b64 v[52:53], 8, v[156:157]
	v_lshl_add_u64 v[52:53], s[16:17], 0, v[52:53]
	v_lshl_add_u64 v[52:53], s[50:51], 2, v[52:53]
	global_store_dwordx2 v[52:53], v[48:49], off

.LBB0_253:
	s_nop 0
	s_nop 0
	v_permlane32_swap_b32_e32 v185, v186
	v_add_f32_e32 v48, v185, v186
	v_fmamk_f32 v48, v48, 0x3a800000, v177
	v_mov_b64_e32 v[54:55], s[30:31]
	s_waitcnt lgkmcnt(1)
	s_waitcnt lgkmcnt(0)
	v_rsq_f32_e32 v50, v48
	s_nop 0
	v_pk_mul_f32 v[44:45], v[44:45], v[50:51] op_sel_hi:[1,0]
	v_pk_mul_f32 v[46:47], v[46:47], v[50:51] op_sel_hi:[1,0]
	v_and_b32_e32 v53, 0x7fffffff, v45
	v_and_b32_e32 v52, 0x7fffffff, v44
	v_pk_fma_f32 v[52:53], v[52:53], s[26:27], 1.0 op_sel_hi:[1,0,0]
	v_pk_mul_f32 v[58:59], v[44:45], v[44:45]
	v_rcp_f32_e32 v52, v52
	v_rcp_f32_e32 v53, v53
	v_pk_mul_f32 v[58:59], v[58:59], s[40:41] op_sel_hi:[1,0]
	v_and_b32_e32 v61, 0x7fffffff, v47
	v_exp_f32_e32 v58, v58
	v_pk_fma_f32 v[56:57], v[52:53], s[28:29], v[54:55] op_sel_hi:[1,0,0]
	v_exp_f32_e32 v59, v59
	v_pk_fma_f32 v[56:57], v[52:53], v[56:57], s[34:35] op_sel_hi:[1,1,0]
	v_and_b32_e32 v60, 0x7fffffff, v46
	v_pk_fma_f32 v[56:57], v[52:53], v[56:57], s[36:37] op_sel_hi:[1,1,0]
	v_pk_fma_f32 v[60:61], v[60:61], s[26:27], 1.0 op_sel_hi:[1,0,0]
	v_pk_fma_f32 v[56:57], v[52:53], v[56:57], s[38:39] op_sel_hi:[1,1,0]
	v_rcp_f32_e32 v60, v60
	v_pk_mul_f32 v[52:53], v[52:53], v[56:57]
	v_rcp_f32_e32 v61, v61
	v_pk_mul_f32 v[52:53], v[58:59], v[52:53]
	v_cmp_gt_f32_e32 vcc, 0, v44
	v_pk_mul_f32 v[58:59], v[44:45], v[52:53]
	v_pk_fma_f32 v[52:53], v[44:45], v[52:53], v[44:45] neg_lo:[1,0,0] neg_hi:[1,0,0]
	v_pk_mul_f32 v[42:43], v[42:43], v[50:51] op_sel_hi:[1,0]
	v_pk_mul_f32 v[40:41], v[40:41], v[50:51] op_sel_hi:[1,0]
	v_pk_mul_f32 v[56:57], v[46:47], v[46:47]
	v_cndmask_b32_e32 v51, v52, v58, vcc
	v_cmp_gt_f32_e32 vcc, 0, v45
	v_pk_fma_f32 v[44:45], v[60:61], s[28:29], v[54:55] op_sel_hi:[1,0,0]
	v_lshlrev_b64 v[48:49], 12, v[154:155]
	v_cndmask_b32_e32 v58, v53, v59, vcc
	v_pk_mul_f32 v[52:53], v[56:57], s[40:41] op_sel_hi:[1,0]
	v_pk_fma_f32 v[44:45], v[60:61], v[44:45], s[34:35] op_sel_hi:[1,1,0]
	v_exp_f32_e32 v52, v52
	v_exp_f32_e32 v53, v53
	v_pk_fma_f32 v[44:45], v[60:61], v[44:45], s[36:37] op_sel_hi:[1,1,0]
	v_and_b32_e32 v57, 0x7fffffff, v41
	v_and_b32_e32 v56, 0x7fffffff, v40
	v_pk_fma_f32 v[44:45], v[60:61], v[44:45], s[38:39] op_sel_hi:[1,1,0]
	v_pk_fma_f32 v[56:57], v[56:57], s[26:27], 1.0 op_sel_hi:[1,0,0]
	v_pk_mul_f32 v[44:45], v[60:61], v[44:45]
	v_rcp_f32_e32 v56, v56
	v_rcp_f32_e32 v57, v57
	v_pk_mul_f32 v[44:45], v[52:53], v[44:45]
	v_max_f32_e32 v59, 0, v46
	v_max_f32_e32 v60, 0, v47
	v_fma_f32 v59, -|v46|, v44, v59
	v_fma_f32 v60, -|v47|, v45, v60
	v_lshl_add_u64 v[48:49], v[152:153], 0, v[48:49]
	v_pk_mul_f32 v[46:47], v[40:41], v[40:41]
	s_nop 0
	v_pk_fma_f32 v[44:45], v[56:57], s[28:29], v[54:55] op_sel_hi:[1,0,0]
	v_pk_mul_f32 v[46:47], v[46:47], s[40:41] op_sel_hi:[1,0]
	v_pk_fma_f32 v[44:45], v[56:57], v[44:45], s[34:35] op_sel_hi:[1,1,0]
	v_exp_f32_e32 v46, v46
	v_pk_fma_f32 v[44:45], v[56:57], v[44:45], s[36:37] op_sel_hi:[1,1,0]
	v_exp_f32_e32 v47, v47
	v_pk_fma_f32 v[44:45], v[56:57], v[44:45], s[38:39] op_sel_hi:[1,1,0]
	v_pk_mul_f32 v[44:45], v[56:57], v[44:45]
	v_and_b32_e32 v57, 0x7fffffff, v43
	v_and_b32_e32 v56, 0x7fffffff, v42
	v_pk_fma_f32 v[56:57], v[56:57], s[26:27], 1.0 op_sel_hi:[1,0,0]
	v_pk_mul_f32 v[44:45], v[46:47], v[44:45]
	v_rcp_f32_e32 v56, v56
	v_rcp_f32_e32 v57, v57
	v_max_f32_e32 v46, 0, v40
	v_max_f32_e32 v47, 0, v41
	v_fma_f32 v46, -|v40|, v44, v46
	v_fma_f32 v47, -|v41|, v45, v47
	v_pk_mul_f32 v[52:53], v[42:43], v[42:43]
	v_pk_fma_f32 v[40:41], v[56:57], s[28:29], v[54:55] op_sel_hi:[1,0,0]
	s_nop 0
	v_pk_mul_f32 v[44:45], v[52:53], s[40:41] op_sel_hi:[1,0]
	v_pk_fma_f32 v[40:41], v[56:57], v[40:41], s[34:35] op_sel_hi:[1,1,0]
	v_exp_f32_e32 v44, v44
	v_exp_f32_e32 v45, v45
	v_pk_fma_f32 v[40:41], v[56:57], v[40:41], s[36:37] op_sel_hi:[1,1,0]
	v_cmp_gt_f32_e32 vcc, 0, v42
	v_pk_fma_f32 v[40:41], v[56:57], v[40:41], s[38:39] op_sel_hi:[1,1,0]
	s_nop 0
	v_pk_mul_f32 v[40:41], v[56:57], v[40:41]
	s_nop 0
	v_pk_mul_f32 v[40:41], v[44:45], v[40:41]
	s_nop 0
	v_pk_mul_f32 v[44:45], v[42:43], v[40:41]
	v_pk_fma_f32 v[40:41], v[42:43], v[40:41], v[42:43] neg_lo:[1,0,0] neg_hi:[1,0,0]
	s_nop 0
	v_cndmask_b32_e32 v44, v40, v44, vcc
	v_cmp_gt_f32_e32 vcc, 0, v43
	v_cvt_pk_bf16_f32 v40, v51, v58
	s_nop 1
	v_cndmask_b32_e32 v43, v41, v45, vcc
	v_cvt_pk_bf16_f32 v41, v59, v60
	v_cvt_pk_bf16_f32 v42, v46, v47
	v_cvt_pk_bf16_f32 v43, v44, v43
	v_mov_b32_e32 v44, 0
	s_and_b64 vcc, exec, s[8:9]
	v_mov_b32_e32 v45, 0
	global_store_dwordx4 v[48:49], v[40:43], off
	s_cbranch_vccnz .LBB0_255
	v_and_b32_e32 v45, 16, v40
	v_and_b32_e32 v44, 0xffff0000, v40
	v_lshlrev_b32_e32 v53, 16, v41
	v_lshlrev_b32_e32 v52, 16, v42
	v_and_b32_e32 v46, 0xffff0000, v41
	v_mov_b32_e32 v47, v44
	v_pk_mov_b32 v[58:59], v[52:53], v[44:45] op_sel:[1,0]
	v_lshlrev_b32_e32 v40, 16, v40
	v_and_b32_e32 v54, 0xffff0000, v43
	v_mov_b32_e32 v55, v46
	v_and_b32_e32 v42, 0xffff0000, v42
	v_lshlrev_b32_e32 v56, 16, v43
	v_mov_b32_e32 v43, v53
	v_mov_b32_e32 v41, v46
	v_mov_b32_e32 v57, v46
	v_pk_add_f32 v[60:61], v[46:47], v[58:59]
	v_pk_mul_f32 v[46:47], v[46:47], v[58:59]
	v_pk_add_f32 v[44:45], v[40:41], v[44:45] op_sel_hi:[0,1]
	v_mov_b32_e32 v61, v47
	v_pk_add_f32 v[46:47], v[52:53], v[42:43]
	v_pk_mul_f32 v[58:59], v[52:53], v[52:53]
	v_mov_b32_e32 v43, v54
	v_mul_f32_e32 v45, v40, v40
	v_mov_b32_e32 v47, v59
	v_pk_add_f32 v[58:59], v[54:55], v[56:57]
	v_pk_mul_f32 v[40:41], v[54:55], v[40:41]
	v_mov_b32_e32 v53, v56
	v_pk_mul_f32 v[42:43], v[42:43], v[42:43]
	v_mov_b32_e32 v59, v41
	v_pk_fma_f32 v[42:43], v[52:53], v[52:53], v[42:43]
	v_pk_add_f32 v[44:45], v[44:45], v[60:61]
	v_pk_add_f32 v[40:41], v[46:47], v[58:59]
	v_pk_add_f32 v[42:43], v[42:43], v[42:43] op_sel_hi:[0,1]
	v_pk_add_f32 v[40:41], v[44:45], v[40:41]
	v_mov_b32_e32 v137, v43
	v_pk_add_f32 v[44:45], v[40:41], v[136:137]
.LBB0_255:
	v_mov_b32_e32 v51, v50
	v_pk_mul_f32 v[36:37], v[36:37], v[50:51]
	v_mov_b32_e32 v40, v50
	v_and_b32_e32 v43, 0x7fffffff, v37
	v_and_b32_e32 v42, 0x7fffffff, v36
	v_pk_fma_f32 v[42:43], v[42:43], s[26:27], 1.0 op_sel_hi:[1,0,0]
	v_mov_b32_e32 v41, v50
	v_rcp_f32_e32 v42, v42
	v_rcp_f32_e32 v43, v43
	v_pk_mul_f32 v[38:39], v[38:39], v[40:41]
	v_pk_mul_f32 v[34:35], v[34:35], v[40:41]
	v_pk_mul_f32 v[32:33], v[32:33], v[50:51]
	v_mov_b64_e32 v[40:41], s[30:31]
	v_pk_mul_f32 v[50:51], v[36:37], v[36:37]
	v_pk_fma_f32 v[46:47], v[42:43], s[28:29], v[40:41] op_sel_hi:[1,0,0]
	v_pk_mul_f32 v[50:51], v[50:51], s[40:41] op_sel_hi:[1,0]
	v_pk_fma_f32 v[46:47], v[42:43], v[46:47], s[34:35] op_sel_hi:[1,1,0]
	v_exp_f32_e32 v50, v50
	v_exp_f32_e32 v51, v51
	v_pk_fma_f32 v[46:47], v[42:43], v[46:47], s[36:37] op_sel_hi:[1,1,0]
	v_and_b32_e32 v53, 0x7fffffff, v39
	v_and_b32_e32 v52, 0x7fffffff, v38
	v_pk_fma_f32 v[46:47], v[42:43], v[46:47], s[38:39] op_sel_hi:[1,1,0]
	v_pk_fma_f32 v[52:53], v[52:53], s[26:27], 1.0 op_sel_hi:[1,0,0]
	v_pk_mul_f32 v[42:43], v[42:43], v[46:47]
	v_rcp_f32_e32 v52, v52
	v_rcp_f32_e32 v53, v53
	v_pk_mul_f32 v[42:43], v[50:51], v[42:43]
	v_max_f32_e32 v50, 0, v36
	v_max_f32_e32 v51, 0, v37
	v_fma_f32 v50, -|v36|, v42, v50
	v_fma_f32 v51, -|v37|, v43, v51
	v_pk_mul_f32 v[46:47], v[38:39], v[38:39]
	v_pk_fma_f32 v[36:37], v[52:53], s[28:29], v[40:41] op_sel_hi:[1,0,0]
	s_nop 0
	v_pk_mul_f32 v[42:43], v[46:47], s[40:41] op_sel_hi:[1,0]
	v_pk_fma_f32 v[36:37], v[52:53], v[36:37], s[34:35] op_sel_hi:[1,1,0]
	v_exp_f32_e32 v42, v42
	v_exp_f32_e32 v43, v43
	v_pk_fma_f32 v[36:37], v[52:53], v[36:37], s[36:37] op_sel_hi:[1,1,0]
	v_and_b32_e32 v47, 0x7fffffff, v33
	v_and_b32_e32 v46, 0x7fffffff, v32
	v_pk_fma_f32 v[36:37], v[52:53], v[36:37], s[38:39] op_sel_hi:[1,1,0]
	v_pk_fma_f32 v[46:47], v[46:47], s[26:27], 1.0 op_sel_hi:[1,0,0]
	v_pk_mul_f32 v[36:37], v[52:53], v[36:37]
	v_rcp_f32_e32 v46, v46
	v_rcp_f32_e32 v47, v47
	v_pk_mul_f32 v[36:37], v[42:43], v[36:37]
	v_max_f32_e32 v52, 0, v38
	v_max_f32_e32 v53, 0, v39
	v_fma_f32 v52, -|v38|, v36, v52
	v_fma_f32 v53, -|v39|, v37, v53
	s_nop 0
	v_pk_mul_f32 v[38:39], v[32:33], v[32:33]
	s_nop 0
	v_pk_fma_f32 v[36:37], v[46:47], s[28:29], v[40:41] op_sel_hi:[1,0,0]
	v_pk_mul_f32 v[38:39], v[38:39], s[40:41] op_sel_hi:[1,0]
	v_pk_fma_f32 v[36:37], v[46:47], v[36:37], s[34:35] op_sel_hi:[1,1,0]
	v_exp_f32_e32 v38, v38
	v_pk_fma_f32 v[36:37], v[46:47], v[36:37], s[36:37] op_sel_hi:[1,1,0]
	v_exp_f32_e32 v39, v39
	v_pk_fma_f32 v[36:37], v[46:47], v[36:37], s[38:39] op_sel_hi:[1,1,0]
	v_pk_mul_f32 v[36:37], v[46:47], v[36:37]
	v_and_b32_e32 v47, 0x7fffffff, v35
	v_and_b32_e32 v46, 0x7fffffff, v34
	v_pk_fma_f32 v[46:47], v[46:47], s[26:27], 1.0 op_sel_hi:[1,0,0]
	v_pk_mul_f32 v[36:37], v[38:39], v[36:37]
	v_rcp_f32_e32 v46, v46
	v_rcp_f32_e32 v47, v47
	v_max_f32_e32 v38, 0, v32
	v_max_f32_e32 v39, 0, v33
	v_fma_f32 v38, -|v32|, v36, v38
	v_fma_f32 v39, -|v33|, v37, v39
	v_pk_mul_f32 v[42:43], v[34:35], v[34:35]
	v_pk_fma_f32 v[32:33], v[46:47], s[28:29], v[40:41] op_sel_hi:[1,0,0]
	s_nop 0
	v_pk_mul_f32 v[36:37], v[42:43], s[40:41] op_sel_hi:[1,0]
	v_pk_fma_f32 v[32:33], v[46:47], v[32:33], s[34:35] op_sel_hi:[1,1,0]
	v_exp_f32_e32 v36, v36
	v_exp_f32_e32 v37, v37
	v_pk_fma_f32 v[32:33], v[46:47], v[32:33], s[36:37] op_sel_hi:[1,1,0]
	v_cmp_gt_f32_e32 vcc, 0, v34
	v_pk_fma_f32 v[32:33], v[46:47], v[32:33], s[38:39] op_sel_hi:[1,1,0]
	s_nop 0
	v_pk_mul_f32 v[32:33], v[46:47], v[32:33]
	s_nop 0
	v_pk_mul_f32 v[32:33], v[36:37], v[32:33]
	s_nop 0
	v_pk_mul_f32 v[36:37], v[34:35], v[32:33]
	v_pk_fma_f32 v[32:33], v[34:35], v[32:33], v[34:35] neg_lo:[1,0,0] neg_hi:[1,0,0]
	s_nop 0
	v_cndmask_b32_e32 v36, v32, v36, vcc
	v_cmp_gt_f32_e32 vcc, 0, v35
	v_cvt_pk_bf16_f32 v32, v50, v51
	s_nop 1
	v_cndmask_b32_e32 v35, v33, v37, vcc
	s_and_b64 vcc, exec, s[8:9]
	v_cvt_pk_bf16_f32 v33, v52, v53
	v_cvt_pk_bf16_f32 v34, v38, v39
	v_cvt_pk_bf16_f32 v35, v36, v35
	global_store_dwordx4 v[48:49], v[32:35], off offset:256
	s_cbranch_vccnz .LBB0_259
	v_lshlrev_b32_e32 v36, 16, v32
	v_and_b32_e32 v32, 0xffff0000, v32
	v_lshlrev_b32_e32 v38, 16, v33
	v_and_b32_e32 v40, 0xffff0000, v33
	v_lshlrev_b32_e32 v42, 16, v34
	v_and_b32_e32 v34, 0xffff0000, v34
	v_lshlrev_b32_e32 v46, 16, v35
	v_and_b32_e32 v48, 0xffff0000, v35
	v_mul_f32_e32 v37, v36, v36
	v_mul_f32_e32 v33, v32, v32
	v_mul_f32_e32 v39, v38, v38
	v_mul_f32_e32 v41, v40, v40
	v_mul_f32_e32 v43, v42, v42
	v_mul_f32_e32 v35, v34, v34
	v_mul_f32_e32 v47, v46, v46
	v_mul_f32_e32 v49, v48, v48
	v_pk_add_f32 v[32:33], v[36:37], v[32:33]
	v_pk_add_f32 v[36:37], v[38:39], v[40:41]
	v_pk_add_f32 v[34:35], v[42:43], v[34:35]
	v_pk_add_f32 v[32:33], v[32:33], v[36:37]
	v_pk_add_f32 v[36:37], v[46:47], v[48:49]
	s_nop 0
	v_pk_add_f32 v[34:35], v[34:35], v[36:37]
	s_nop 0
	v_pk_add_f32 v[32:33], v[32:33], v[34:35]
	s_nop 0
	v_pk_add_f32 v[32:33], v[44:45], v[32:33]
	s_nop 0
	v_mov_b32_e32 v34, v32
	v_mov_b32_e32 v35, v33
	s_nop 0
	v_permlane16_swap_b32_e32 v32, v34
	v_permlane16_swap_b32_e32 v33, v35
	v_pk_add_f32 v[32:33], v[32:33], v[34:35]
	s_nop 0
	v_mov_b32_e32 v34, v32
	v_mov_b32_e32 v35, v33
	s_nop 0
	v_permlane32_swap_b32_e32 v32, v34
	v_permlane32_swap_b32_e32 v33, v35
	v_pk_add_f32 v[32:33], v[32:33], v[34:35]
	s_and_saveexec_b64 s[10:11], s[4:5]
	s_cbranch_execz .LBB0_258
	v_lshlrev_b64 v[36:37], 8, v[154:155]
	v_lshl_add_u64 v[36:37], s[16:17], 0, v[36:37]
	v_lshl_add_u64 v[36:37], s[50:51], 2, v[36:37]
	global_store_dwordx2 v[36:37], v[32:33], off

.LBB0_259:
	s_nop 0
	s_nop 0
	v_permlane32_swap_b32_e32 v183, v184
	v_add_f32_e32 v32, v183, v184
	v_fmamk_f32 v32, v32, 0x3a800000, v177
	v_mov_b64_e32 v[38:39], s[30:31]
	s_waitcnt lgkmcnt(1)
	s_waitcnt lgkmcnt(0)
	v_rsq_f32_e32 v34, v32
	s_nop 0
	v_pk_mul_f32 v[28:29], v[28:29], v[34:35] op_sel_hi:[1,0]
	v_pk_mul_f32 v[30:31], v[30:31], v[34:35] op_sel_hi:[1,0]
	v_and_b32_e32 v37, 0x7fffffff, v29
	v_and_b32_e32 v36, 0x7fffffff, v28
	v_pk_fma_f32 v[36:37], v[36:37], s[26:27], 1.0 op_sel_hi:[1,0,0]
	v_pk_mul_f32 v[42:43], v[28:29], v[28:29]
	v_rcp_f32_e32 v36, v36
	v_rcp_f32_e32 v37, v37
	v_pk_mul_f32 v[42:43], v[42:43], s[40:41] op_sel_hi:[1,0]
	v_and_b32_e32 v45, 0x7fffffff, v31
	v_exp_f32_e32 v42, v42
	v_pk_fma_f32 v[40:41], v[36:37], s[28:29], v[38:39] op_sel_hi:[1,0,0]
	v_exp_f32_e32 v43, v43
	v_pk_fma_f32 v[40:41], v[36:37], v[40:41], s[34:35] op_sel_hi:[1,1,0]
	v_and_b32_e32 v44, 0x7fffffff, v30
	v_pk_fma_f32 v[40:41], v[36:37], v[40:41], s[36:37] op_sel_hi:[1,1,0]
	v_pk_fma_f32 v[44:45], v[44:45], s[26:27], 1.0 op_sel_hi:[1,0,0]
	v_pk_fma_f32 v[40:41], v[36:37], v[40:41], s[38:39] op_sel_hi:[1,1,0]
	v_rcp_f32_e32 v44, v44
	v_pk_mul_f32 v[36:37], v[36:37], v[40:41]
	v_rcp_f32_e32 v45, v45
	v_pk_mul_f32 v[36:37], v[42:43], v[36:37]
	v_cmp_gt_f32_e32 vcc, 0, v28
	v_pk_mul_f32 v[42:43], v[28:29], v[36:37]
	v_pk_fma_f32 v[36:37], v[28:29], v[36:37], v[28:29] neg_lo:[1,0,0] neg_hi:[1,0,0]
	v_pk_mul_f32 v[26:27], v[26:27], v[34:35] op_sel_hi:[1,0]
	v_pk_mul_f32 v[24:25], v[24:25], v[34:35] op_sel_hi:[1,0]
	v_pk_mul_f32 v[40:41], v[30:31], v[30:31]
	v_cndmask_b32_e32 v35, v36, v42, vcc
	v_cmp_gt_f32_e32 vcc, 0, v29
	v_pk_fma_f32 v[28:29], v[44:45], s[28:29], v[38:39] op_sel_hi:[1,0,0]
	v_lshlrev_b64 v[32:33], 12, v[150:151]
	v_cndmask_b32_e32 v42, v37, v43, vcc
	v_pk_mul_f32 v[36:37], v[40:41], s[40:41] op_sel_hi:[1,0]
	v_pk_fma_f32 v[28:29], v[44:45], v[28:29], s[34:35] op_sel_hi:[1,1,0]
	v_exp_f32_e32 v36, v36
	v_exp_f32_e32 v37, v37
	v_pk_fma_f32 v[28:29], v[44:45], v[28:29], s[36:37] op_sel_hi:[1,1,0]
	v_and_b32_e32 v41, 0x7fffffff, v25
	v_and_b32_e32 v40, 0x7fffffff, v24
	v_pk_fma_f32 v[28:29], v[44:45], v[28:29], s[38:39] op_sel_hi:[1,1,0]
	v_pk_fma_f32 v[40:41], v[40:41], s[26:27], 1.0 op_sel_hi:[1,0,0]
	v_pk_mul_f32 v[28:29], v[44:45], v[28:29]
	v_rcp_f32_e32 v40, v40
	v_rcp_f32_e32 v41, v41
	v_pk_mul_f32 v[28:29], v[36:37], v[28:29]
	v_max_f32_e32 v43, 0, v30
	v_max_f32_e32 v44, 0, v31
	v_fma_f32 v43, -|v30|, v28, v43
	v_fma_f32 v44, -|v31|, v29, v44
	v_lshl_add_u64 v[32:33], v[152:153], 0, v[32:33]
	v_pk_mul_f32 v[30:31], v[24:25], v[24:25]
	s_nop 0
	v_pk_fma_f32 v[28:29], v[40:41], s[28:29], v[38:39] op_sel_hi:[1,0,0]
	v_pk_mul_f32 v[30:31], v[30:31], s[40:41] op_sel_hi:[1,0]
	v_pk_fma_f32 v[28:29], v[40:41], v[28:29], s[34:35] op_sel_hi:[1,1,0]
	v_exp_f32_e32 v30, v30
	v_pk_fma_f32 v[28:29], v[40:41], v[28:29], s[36:37] op_sel_hi:[1,1,0]
	v_exp_f32_e32 v31, v31
	v_pk_fma_f32 v[28:29], v[40:41], v[28:29], s[38:39] op_sel_hi:[1,1,0]
	v_pk_mul_f32 v[28:29], v[40:41], v[28:29]
	v_and_b32_e32 v41, 0x7fffffff, v27
	v_and_b32_e32 v40, 0x7fffffff, v26
	v_pk_fma_f32 v[40:41], v[40:41], s[26:27], 1.0 op_sel_hi:[1,0,0]
	v_pk_mul_f32 v[28:29], v[30:31], v[28:29]
	v_rcp_f32_e32 v40, v40
	v_rcp_f32_e32 v41, v41
	v_max_f32_e32 v30, 0, v24
	v_max_f32_e32 v31, 0, v25
	v_fma_f32 v30, -|v24|, v28, v30
	v_fma_f32 v31, -|v25|, v29, v31
	v_pk_mul_f32 v[36:37], v[26:27], v[26:27]
	v_pk_fma_f32 v[24:25], v[40:41], s[28:29], v[38:39] op_sel_hi:[1,0,0]
	s_nop 0
	v_pk_mul_f32 v[28:29], v[36:37], s[40:41] op_sel_hi:[1,0]
	v_pk_fma_f32 v[24:25], v[40:41], v[24:25], s[34:35] op_sel_hi:[1,1,0]
	v_exp_f32_e32 v28, v28
	v_exp_f32_e32 v29, v29
	v_pk_fma_f32 v[24:25], v[40:41], v[24:25], s[36:37] op_sel_hi:[1,1,0]
	v_cmp_gt_f32_e32 vcc, 0, v26
	v_pk_fma_f32 v[24:25], v[40:41], v[24:25], s[38:39] op_sel_hi:[1,1,0]
	s_nop 0
	v_pk_mul_f32 v[24:25], v[40:41], v[24:25]
	s_nop 0
	v_pk_mul_f32 v[24:25], v[28:29], v[24:25]
	s_nop 0
	v_pk_mul_f32 v[28:29], v[26:27], v[24:25]
	v_pk_fma_f32 v[24:25], v[26:27], v[24:25], v[26:27] neg_lo:[1,0,0] neg_hi:[1,0,0]
	s_nop 0
	v_cndmask_b32_e32 v28, v24, v28, vcc
	v_cmp_gt_f32_e32 vcc, 0, v27
	v_cvt_pk_bf16_f32 v24, v35, v42
	s_nop 1
	v_cndmask_b32_e32 v27, v25, v29, vcc
	v_cvt_pk_bf16_f32 v25, v43, v44
	v_cvt_pk_bf16_f32 v26, v30, v31
	v_cvt_pk_bf16_f32 v27, v28, v27
	v_mov_b32_e32 v28, 0
	s_and_b64 vcc, exec, s[8:9]
	v_mov_b32_e32 v29, 0
	global_store_dwordx4 v[32:33], v[24:27], off
	s_cbranch_vccnz .LBB0_261
	v_and_b32_e32 v29, 16, v24
	v_and_b32_e32 v28, 0xffff0000, v24
	v_lshlrev_b32_e32 v37, 16, v25
	v_lshlrev_b32_e32 v36, 16, v26
	v_and_b32_e32 v30, 0xffff0000, v25
	v_mov_b32_e32 v31, v28
	v_pk_mov_b32 v[42:43], v[36:37], v[28:29] op_sel:[1,0]
	v_lshlrev_b32_e32 v24, 16, v24
	v_and_b32_e32 v38, 0xffff0000, v27
	v_mov_b32_e32 v39, v30
	v_and_b32_e32 v26, 0xffff0000, v26
	v_lshlrev_b32_e32 v40, 16, v27
	v_mov_b32_e32 v27, v37
	v_mov_b32_e32 v25, v30
	v_mov_b32_e32 v41, v30
	v_pk_add_f32 v[44:45], v[30:31], v[42:43]
	v_pk_mul_f32 v[30:31], v[30:31], v[42:43]
	v_pk_add_f32 v[28:29], v[24:25], v[28:29] op_sel_hi:[0,1]
	v_mov_b32_e32 v45, v31
	v_pk_add_f32 v[30:31], v[36:37], v[26:27]
	v_pk_mul_f32 v[42:43], v[36:37], v[36:37]
	v_mov_b32_e32 v27, v38
	v_mul_f32_e32 v29, v24, v24
	v_mov_b32_e32 v31, v43
	v_pk_add_f32 v[42:43], v[38:39], v[40:41]
	v_pk_mul_f32 v[24:25], v[38:39], v[24:25]
	v_mov_b32_e32 v37, v40
	v_pk_mul_f32 v[26:27], v[26:27], v[26:27]
	v_mov_b32_e32 v43, v25
	v_pk_fma_f32 v[26:27], v[36:37], v[36:37], v[26:27]
	v_pk_add_f32 v[28:29], v[28:29], v[44:45]
	v_pk_add_f32 v[24:25], v[30:31], v[42:43]
	v_pk_add_f32 v[26:27], v[26:27], v[26:27] op_sel_hi:[0,1]
	v_pk_add_f32 v[24:25], v[28:29], v[24:25]
	v_mov_b32_e32 v137, v27
	v_pk_add_f32 v[28:29], v[24:25], v[136:137]
.LBB0_261:
	v_mov_b32_e32 v35, v34
	v_pk_mul_f32 v[20:21], v[20:21], v[34:35]
	v_mov_b32_e32 v24, v34
	v_and_b32_e32 v27, 0x7fffffff, v21
	v_and_b32_e32 v26, 0x7fffffff, v20
	v_pk_fma_f32 v[26:27], v[26:27], s[26:27], 1.0 op_sel_hi:[1,0,0]
	v_mov_b32_e32 v25, v34
	v_rcp_f32_e32 v26, v26
	v_rcp_f32_e32 v27, v27
	v_pk_mul_f32 v[22:23], v[22:23], v[24:25]
	v_pk_mul_f32 v[18:19], v[18:19], v[24:25]
	v_pk_mul_f32 v[16:17], v[16:17], v[34:35]
	v_mov_b64_e32 v[24:25], s[30:31]
	v_pk_mul_f32 v[34:35], v[20:21], v[20:21]
	v_pk_fma_f32 v[30:31], v[26:27], s[28:29], v[24:25] op_sel_hi:[1,0,0]
	v_pk_mul_f32 v[34:35], v[34:35], s[40:41] op_sel_hi:[1,0]
	v_pk_fma_f32 v[30:31], v[26:27], v[30:31], s[34:35] op_sel_hi:[1,1,0]
	v_exp_f32_e32 v34, v34
	v_exp_f32_e32 v35, v35
	v_pk_fma_f32 v[30:31], v[26:27], v[30:31], s[36:37] op_sel_hi:[1,1,0]
	v_and_b32_e32 v37, 0x7fffffff, v23
	v_and_b32_e32 v36, 0x7fffffff, v22
	v_pk_fma_f32 v[30:31], v[26:27], v[30:31], s[38:39] op_sel_hi:[1,1,0]
	v_pk_fma_f32 v[36:37], v[36:37], s[26:27], 1.0 op_sel_hi:[1,0,0]
	v_pk_mul_f32 v[26:27], v[26:27], v[30:31]
	v_rcp_f32_e32 v36, v36
	v_rcp_f32_e32 v37, v37
	v_pk_mul_f32 v[26:27], v[34:35], v[26:27]
	v_max_f32_e32 v34, 0, v20
	v_max_f32_e32 v35, 0, v21
	v_fma_f32 v34, -|v20|, v26, v34
	v_fma_f32 v35, -|v21|, v27, v35
	v_pk_mul_f32 v[30:31], v[22:23], v[22:23]
	v_pk_fma_f32 v[20:21], v[36:37], s[28:29], v[24:25] op_sel_hi:[1,0,0]
	s_nop 0
	v_pk_mul_f32 v[26:27], v[30:31], s[40:41] op_sel_hi:[1,0]
	v_pk_fma_f32 v[20:21], v[36:37], v[20:21], s[34:35] op_sel_hi:[1,1,0]
	v_exp_f32_e32 v26, v26
	v_exp_f32_e32 v27, v27
	v_pk_fma_f32 v[20:21], v[36:37], v[20:21], s[36:37] op_sel_hi:[1,1,0]
	v_and_b32_e32 v31, 0x7fffffff, v17
	v_and_b32_e32 v30, 0x7fffffff, v16
	v_pk_fma_f32 v[20:21], v[36:37], v[20:21], s[38:39] op_sel_hi:[1,1,0]
	v_pk_fma_f32 v[30:31], v[30:31], s[26:27], 1.0 op_sel_hi:[1,0,0]
	v_pk_mul_f32 v[20:21], v[36:37], v[20:21]
	v_rcp_f32_e32 v30, v30
	v_rcp_f32_e32 v31, v31
	v_pk_mul_f32 v[20:21], v[26:27], v[20:21]
	v_max_f32_e32 v36, 0, v22
	v_max_f32_e32 v37, 0, v23
	v_fma_f32 v36, -|v22|, v20, v36
	v_fma_f32 v37, -|v23|, v21, v37
	s_nop 0
	v_pk_mul_f32 v[22:23], v[16:17], v[16:17]
	s_nop 0
	v_pk_fma_f32 v[20:21], v[30:31], s[28:29], v[24:25] op_sel_hi:[1,0,0]
	v_pk_mul_f32 v[22:23], v[22:23], s[40:41] op_sel_hi:[1,0]
	v_pk_fma_f32 v[20:21], v[30:31], v[20:21], s[34:35] op_sel_hi:[1,1,0]
	v_exp_f32_e32 v22, v22
	v_pk_fma_f32 v[20:21], v[30:31], v[20:21], s[36:37] op_sel_hi:[1,1,0]
	v_exp_f32_e32 v23, v23
	v_pk_fma_f32 v[20:21], v[30:31], v[20:21], s[38:39] op_sel_hi:[1,1,0]
	v_pk_mul_f32 v[20:21], v[30:31], v[20:21]
	v_and_b32_e32 v31, 0x7fffffff, v19
	v_and_b32_e32 v30, 0x7fffffff, v18
	v_pk_fma_f32 v[30:31], v[30:31], s[26:27], 1.0 op_sel_hi:[1,0,0]
	v_pk_mul_f32 v[20:21], v[22:23], v[20:21]
	v_rcp_f32_e32 v30, v30
	v_rcp_f32_e32 v31, v31
	v_max_f32_e32 v22, 0, v16
	v_max_f32_e32 v23, 0, v17
	v_fma_f32 v22, -|v16|, v20, v22
	v_fma_f32 v23, -|v17|, v21, v23
	v_pk_mul_f32 v[26:27], v[18:19], v[18:19]
	v_pk_fma_f32 v[16:17], v[30:31], s[28:29], v[24:25] op_sel_hi:[1,0,0]
	s_nop 0
	v_pk_mul_f32 v[20:21], v[26:27], s[40:41] op_sel_hi:[1,0]
	v_pk_fma_f32 v[16:17], v[30:31], v[16:17], s[34:35] op_sel_hi:[1,1,0]
	v_exp_f32_e32 v20, v20
	v_exp_f32_e32 v21, v21
	v_pk_fma_f32 v[16:17], v[30:31], v[16:17], s[36:37] op_sel_hi:[1,1,0]
	v_cmp_gt_f32_e32 vcc, 0, v18
	v_pk_fma_f32 v[16:17], v[30:31], v[16:17], s[38:39] op_sel_hi:[1,1,0]
	s_nop 0
	v_pk_mul_f32 v[16:17], v[30:31], v[16:17]
	s_nop 0
	v_pk_mul_f32 v[16:17], v[20:21], v[16:17]
	s_nop 0
	v_pk_mul_f32 v[20:21], v[18:19], v[16:17]
	v_pk_fma_f32 v[16:17], v[18:19], v[16:17], v[18:19] neg_lo:[1,0,0] neg_hi:[1,0,0]
	s_nop 0
	v_cndmask_b32_e32 v20, v16, v20, vcc
	v_cmp_gt_f32_e32 vcc, 0, v19
	v_cvt_pk_bf16_f32 v16, v34, v35
	s_nop 1
	v_cndmask_b32_e32 v19, v17, v21, vcc
	s_and_b64 vcc, exec, s[8:9]
	v_cvt_pk_bf16_f32 v17, v36, v37
	v_cvt_pk_bf16_f32 v18, v22, v23
	v_cvt_pk_bf16_f32 v19, v20, v19
	global_store_dwordx4 v[32:33], v[16:19], off offset:256
	s_cbranch_vccnz .LBB0_265
	v_lshlrev_b32_e32 v20, 16, v16
	v_and_b32_e32 v16, 0xffff0000, v16
	v_lshlrev_b32_e32 v22, 16, v17
	v_and_b32_e32 v24, 0xffff0000, v17
	v_lshlrev_b32_e32 v26, 16, v18
	v_and_b32_e32 v18, 0xffff0000, v18
	v_lshlrev_b32_e32 v30, 16, v19
	v_and_b32_e32 v32, 0xffff0000, v19
	v_mul_f32_e32 v21, v20, v20
	v_mul_f32_e32 v17, v16, v16
	v_mul_f32_e32 v23, v22, v22
	v_mul_f32_e32 v25, v24, v24
	v_mul_f32_e32 v27, v26, v26
	v_mul_f32_e32 v19, v18, v18
	v_mul_f32_e32 v31, v30, v30
	v_mul_f32_e32 v33, v32, v32
	v_pk_add_f32 v[16:17], v[20:21], v[16:17]
	v_pk_add_f32 v[20:21], v[22:23], v[24:25]
	v_pk_add_f32 v[18:19], v[26:27], v[18:19]
	v_pk_add_f32 v[16:17], v[16:17], v[20:21]
	v_pk_add_f32 v[20:21], v[30:31], v[32:33]
	s_nop 0
	v_pk_add_f32 v[18:19], v[18:19], v[20:21]
	s_nop 0
	v_pk_add_f32 v[16:17], v[16:17], v[18:19]
	s_nop 0
	v_pk_add_f32 v[16:17], v[28:29], v[16:17]
	s_nop 0
	v_mov_b32_e32 v18, v16
	v_mov_b32_e32 v19, v17
	s_nop 0
	v_permlane16_swap_b32_e32 v16, v18
	v_permlane16_swap_b32_e32 v17, v19
	v_pk_add_f32 v[16:17], v[16:17], v[18:19]
	s_nop 0
	v_mov_b32_e32 v18, v16
	v_mov_b32_e32 v19, v17
	s_nop 0
	v_permlane32_swap_b32_e32 v16, v18
	v_permlane32_swap_b32_e32 v17, v19
	v_pk_add_f32 v[16:17], v[16:17], v[18:19]
	s_and_saveexec_b64 s[10:11], s[4:5]
	s_cbranch_execz .LBB0_264
	v_lshlrev_b64 v[20:21], 8, v[150:151]
	v_lshl_add_u64 v[20:21], s[16:17], 0, v[20:21]
	v_lshl_add_u64 v[20:21], s[50:51], 2, v[20:21]
	global_store_dwordx2 v[20:21], v[16:17], off

.LBB0_265:
	s_nop 0
	s_nop 0
	v_permlane32_swap_b32_e32 v181, v182
	v_add_f32_e32 v16, v181, v182
	v_fmamk_f32 v16, v16, 0x3a800000, v177
	v_mov_b64_e32 v[22:23], s[30:31]
	s_waitcnt lgkmcnt(1)
	s_waitcnt lgkmcnt(0)
	v_rsq_f32_e32 v18, v16
	s_nop 0
	v_pk_mul_f32 v[12:13], v[12:13], v[18:19] op_sel_hi:[1,0]
	v_pk_mul_f32 v[14:15], v[14:15], v[18:19] op_sel_hi:[1,0]
	v_and_b32_e32 v21, 0x7fffffff, v13
	v_and_b32_e32 v20, 0x7fffffff, v12
	v_pk_fma_f32 v[20:21], v[20:21], s[26:27], 1.0 op_sel_hi:[1,0,0]
	v_pk_mul_f32 v[26:27], v[12:13], v[12:13]
	v_rcp_f32_e32 v20, v20
	v_rcp_f32_e32 v21, v21
	v_pk_mul_f32 v[26:27], v[26:27], s[40:41] op_sel_hi:[1,0]
	v_and_b32_e32 v29, 0x7fffffff, v15
	v_exp_f32_e32 v26, v26
	v_pk_fma_f32 v[24:25], v[20:21], s[28:29], v[22:23] op_sel_hi:[1,0,0]
	v_exp_f32_e32 v27, v27
	v_pk_fma_f32 v[24:25], v[20:21], v[24:25], s[34:35] op_sel_hi:[1,1,0]
	v_and_b32_e32 v28, 0x7fffffff, v14
	v_pk_fma_f32 v[24:25], v[20:21], v[24:25], s[36:37] op_sel_hi:[1,1,0]
	v_pk_fma_f32 v[28:29], v[28:29], s[26:27], 1.0 op_sel_hi:[1,0,0]
	v_pk_fma_f32 v[24:25], v[20:21], v[24:25], s[38:39] op_sel_hi:[1,1,0]
	v_rcp_f32_e32 v28, v28
	v_pk_mul_f32 v[20:21], v[20:21], v[24:25]
	v_rcp_f32_e32 v29, v29
	v_pk_mul_f32 v[20:21], v[26:27], v[20:21]
	v_cmp_gt_f32_e32 vcc, 0, v12
	v_pk_mul_f32 v[26:27], v[12:13], v[20:21]
	v_pk_fma_f32 v[20:21], v[12:13], v[20:21], v[12:13] neg_lo:[1,0,0] neg_hi:[1,0,0]
	v_pk_mul_f32 v[10:11], v[10:11], v[18:19] op_sel_hi:[1,0]
	v_pk_mul_f32 v[8:9], v[8:9], v[18:19] op_sel_hi:[1,0]
	v_pk_mul_f32 v[24:25], v[14:15], v[14:15]
	v_cndmask_b32_e32 v19, v20, v26, vcc
	v_cmp_gt_f32_e32 vcc, 0, v13
	v_pk_fma_f32 v[12:13], v[28:29], s[28:29], v[22:23] op_sel_hi:[1,0,0]
	v_lshlrev_b64 v[16:17], 12, v[148:149]
	v_cndmask_b32_e32 v26, v21, v27, vcc
	v_pk_mul_f32 v[20:21], v[24:25], s[40:41] op_sel_hi:[1,0]
	v_pk_fma_f32 v[12:13], v[28:29], v[12:13], s[34:35] op_sel_hi:[1,1,0]
	v_exp_f32_e32 v20, v20
	v_exp_f32_e32 v21, v21
	v_pk_fma_f32 v[12:13], v[28:29], v[12:13], s[36:37] op_sel_hi:[1,1,0]
	v_and_b32_e32 v25, 0x7fffffff, v9
	v_and_b32_e32 v24, 0x7fffffff, v8
	v_pk_fma_f32 v[12:13], v[28:29], v[12:13], s[38:39] op_sel_hi:[1,1,0]
	v_pk_fma_f32 v[24:25], v[24:25], s[26:27], 1.0 op_sel_hi:[1,0,0]
	v_pk_mul_f32 v[12:13], v[28:29], v[12:13]
	v_rcp_f32_e32 v24, v24
	v_rcp_f32_e32 v25, v25
	v_pk_mul_f32 v[12:13], v[20:21], v[12:13]
	v_max_f32_e32 v27, 0, v14
	v_max_f32_e32 v28, 0, v15
	v_fma_f32 v27, -|v14|, v12, v27
	v_fma_f32 v28, -|v15|, v13, v28
	v_lshl_add_u64 v[16:17], v[152:153], 0, v[16:17]
	v_pk_mul_f32 v[14:15], v[8:9], v[8:9]
	s_nop 0
	v_pk_fma_f32 v[12:13], v[24:25], s[28:29], v[22:23] op_sel_hi:[1,0,0]
	v_pk_mul_f32 v[14:15], v[14:15], s[40:41] op_sel_hi:[1,0]
	v_pk_fma_f32 v[12:13], v[24:25], v[12:13], s[34:35] op_sel_hi:[1,1,0]
	v_exp_f32_e32 v14, v14
	v_pk_fma_f32 v[12:13], v[24:25], v[12:13], s[36:37] op_sel_hi:[1,1,0]
	v_exp_f32_e32 v15, v15
	v_pk_fma_f32 v[12:13], v[24:25], v[12:13], s[38:39] op_sel_hi:[1,1,0]
	v_pk_mul_f32 v[12:13], v[24:25], v[12:13]
	v_and_b32_e32 v25, 0x7fffffff, v11
	v_and_b32_e32 v24, 0x7fffffff, v10
	v_pk_fma_f32 v[24:25], v[24:25], s[26:27], 1.0 op_sel_hi:[1,0,0]
	v_pk_mul_f32 v[12:13], v[14:15], v[12:13]
	v_rcp_f32_e32 v24, v24
	v_rcp_f32_e32 v25, v25
	v_max_f32_e32 v14, 0, v8
	v_max_f32_e32 v15, 0, v9
	v_fma_f32 v14, -|v8|, v12, v14
	v_fma_f32 v15, -|v9|, v13, v15
	v_pk_mul_f32 v[20:21], v[10:11], v[10:11]
	v_pk_fma_f32 v[8:9], v[24:25], s[28:29], v[22:23] op_sel_hi:[1,0,0]
	s_nop 0
	v_pk_mul_f32 v[12:13], v[20:21], s[40:41] op_sel_hi:[1,0]
	v_pk_fma_f32 v[8:9], v[24:25], v[8:9], s[34:35] op_sel_hi:[1,1,0]
	v_exp_f32_e32 v12, v12
	v_exp_f32_e32 v13, v13
	v_pk_fma_f32 v[8:9], v[24:25], v[8:9], s[36:37] op_sel_hi:[1,1,0]
	v_cmp_gt_f32_e32 vcc, 0, v10
	v_pk_fma_f32 v[8:9], v[24:25], v[8:9], s[38:39] op_sel_hi:[1,1,0]
	s_nop 0
	v_pk_mul_f32 v[8:9], v[24:25], v[8:9]
	s_nop 0
	v_pk_mul_f32 v[8:9], v[12:13], v[8:9]
	s_nop 0
	v_pk_mul_f32 v[12:13], v[10:11], v[8:9]
	v_pk_fma_f32 v[8:9], v[10:11], v[8:9], v[10:11] neg_lo:[1,0,0] neg_hi:[1,0,0]
	s_nop 0
	v_cndmask_b32_e32 v12, v8, v12, vcc
	v_cmp_gt_f32_e32 vcc, 0, v11
	v_cvt_pk_bf16_f32 v8, v19, v26
	s_nop 1
	v_cndmask_b32_e32 v11, v9, v13, vcc
	v_cvt_pk_bf16_f32 v9, v27, v28
	v_cvt_pk_bf16_f32 v10, v14, v15
	v_cvt_pk_bf16_f32 v11, v12, v11
	v_mov_b32_e32 v12, 0
	s_and_b64 vcc, exec, s[8:9]
	v_mov_b32_e32 v13, 0
	global_store_dwordx4 v[16:17], v[8:11], off
	s_cbranch_vccnz .LBB0_267
	v_and_b32_e32 v13, 16, v8
	v_and_b32_e32 v12, 0xffff0000, v8
	v_lshlrev_b32_e32 v21, 16, v9
	v_lshlrev_b32_e32 v20, 16, v10
	v_and_b32_e32 v14, 0xffff0000, v9
	v_mov_b32_e32 v15, v12
	v_pk_mov_b32 v[26:27], v[20:21], v[12:13] op_sel:[1,0]
	v_lshlrev_b32_e32 v8, 16, v8
	v_and_b32_e32 v22, 0xffff0000, v11
	v_mov_b32_e32 v23, v14
	v_and_b32_e32 v10, 0xffff0000, v10
	v_lshlrev_b32_e32 v24, 16, v11
	v_mov_b32_e32 v11, v21
	v_mov_b32_e32 v9, v14
	v_mov_b32_e32 v25, v14
	v_pk_add_f32 v[28:29], v[14:15], v[26:27]
	v_pk_mul_f32 v[14:15], v[14:15], v[26:27]
	v_pk_add_f32 v[12:13], v[8:9], v[12:13] op_sel_hi:[0,1]
	v_mov_b32_e32 v29, v15
	v_pk_add_f32 v[14:15], v[20:21], v[10:11]
	v_pk_mul_f32 v[26:27], v[20:21], v[20:21]
	v_mov_b32_e32 v11, v22
	v_mul_f32_e32 v13, v8, v8
	v_mov_b32_e32 v15, v27
	v_pk_add_f32 v[26:27], v[22:23], v[24:25]
	v_pk_mul_f32 v[8:9], v[22:23], v[8:9]
	v_mov_b32_e32 v21, v24
	v_pk_mul_f32 v[10:11], v[10:11], v[10:11]
	v_mov_b32_e32 v27, v9
	v_pk_fma_f32 v[10:11], v[20:21], v[20:21], v[10:11]
	v_pk_add_f32 v[12:13], v[12:13], v[28:29]
	v_pk_add_f32 v[8:9], v[14:15], v[26:27]
	v_pk_add_f32 v[10:11], v[10:11], v[10:11] op_sel_hi:[0,1]
	v_pk_add_f32 v[8:9], v[12:13], v[8:9]
	v_mov_b32_e32 v137, v11
	v_pk_add_f32 v[12:13], v[8:9], v[136:137]
.LBB0_267:
	v_mov_b32_e32 v19, v18
	v_pk_mul_f32 v[4:5], v[4:5], v[18:19]
	v_mov_b32_e32 v8, v18
	v_and_b32_e32 v11, 0x7fffffff, v5
	v_and_b32_e32 v10, 0x7fffffff, v4
	v_pk_fma_f32 v[10:11], v[10:11], s[26:27], 1.0 op_sel_hi:[1,0,0]
	v_mov_b32_e32 v9, v18
	v_rcp_f32_e32 v10, v10
	v_rcp_f32_e32 v11, v11
	v_pk_mul_f32 v[6:7], v[6:7], v[8:9]
	v_pk_mul_f32 v[2:3], v[2:3], v[8:9]
	v_pk_mul_f32 v[0:1], v[0:1], v[18:19]
	v_mov_b64_e32 v[8:9], s[30:31]
	v_pk_mul_f32 v[18:19], v[4:5], v[4:5]
	v_pk_fma_f32 v[14:15], v[10:11], s[28:29], v[8:9] op_sel_hi:[1,0,0]
	v_pk_mul_f32 v[18:19], v[18:19], s[40:41] op_sel_hi:[1,0]
	v_pk_fma_f32 v[14:15], v[10:11], v[14:15], s[34:35] op_sel_hi:[1,1,0]
	v_exp_f32_e32 v18, v18
	v_exp_f32_e32 v19, v19
	v_pk_fma_f32 v[14:15], v[10:11], v[14:15], s[36:37] op_sel_hi:[1,1,0]
	v_and_b32_e32 v21, 0x7fffffff, v7
	v_and_b32_e32 v20, 0x7fffffff, v6
	v_pk_fma_f32 v[14:15], v[10:11], v[14:15], s[38:39] op_sel_hi:[1,1,0]
	v_pk_fma_f32 v[20:21], v[20:21], s[26:27], 1.0 op_sel_hi:[1,0,0]
	v_pk_mul_f32 v[10:11], v[10:11], v[14:15]
	v_rcp_f32_e32 v20, v20
	v_rcp_f32_e32 v21, v21
	v_pk_mul_f32 v[10:11], v[18:19], v[10:11]
	v_max_f32_e32 v18, 0, v4
	v_max_f32_e32 v19, 0, v5
	v_fma_f32 v18, -|v4|, v10, v18
	v_fma_f32 v19, -|v5|, v11, v19
	v_pk_mul_f32 v[14:15], v[6:7], v[6:7]
	v_pk_fma_f32 v[4:5], v[20:21], s[28:29], v[8:9] op_sel_hi:[1,0,0]
	s_nop 0
	v_pk_mul_f32 v[10:11], v[14:15], s[40:41] op_sel_hi:[1,0]
	v_pk_fma_f32 v[4:5], v[20:21], v[4:5], s[34:35] op_sel_hi:[1,1,0]
	v_exp_f32_e32 v10, v10
	v_exp_f32_e32 v11, v11
	v_pk_fma_f32 v[4:5], v[20:21], v[4:5], s[36:37] op_sel_hi:[1,1,0]
	v_and_b32_e32 v15, 0x7fffffff, v1
	v_and_b32_e32 v14, 0x7fffffff, v0
	v_pk_fma_f32 v[4:5], v[20:21], v[4:5], s[38:39] op_sel_hi:[1,1,0]
	v_pk_fma_f32 v[14:15], v[14:15], s[26:27], 1.0 op_sel_hi:[1,0,0]
	v_pk_mul_f32 v[4:5], v[20:21], v[4:5]
	v_rcp_f32_e32 v14, v14
	v_rcp_f32_e32 v15, v15
	v_pk_mul_f32 v[4:5], v[10:11], v[4:5]
	v_max_f32_e32 v20, 0, v6
	v_max_f32_e32 v21, 0, v7
	v_fma_f32 v20, -|v6|, v4, v20
	v_fma_f32 v21, -|v7|, v5, v21
	s_nop 0
	v_pk_mul_f32 v[6:7], v[0:1], v[0:1]
	s_nop 0
	v_pk_fma_f32 v[4:5], v[14:15], s[28:29], v[8:9] op_sel_hi:[1,0,0]
	v_pk_mul_f32 v[6:7], v[6:7], s[40:41] op_sel_hi:[1,0]
	v_pk_fma_f32 v[4:5], v[14:15], v[4:5], s[34:35] op_sel_hi:[1,1,0]
	v_exp_f32_e32 v6, v6
	v_pk_fma_f32 v[4:5], v[14:15], v[4:5], s[36:37] op_sel_hi:[1,1,0]
	v_exp_f32_e32 v7, v7
	v_pk_fma_f32 v[4:5], v[14:15], v[4:5], s[38:39] op_sel_hi:[1,1,0]
	v_pk_mul_f32 v[4:5], v[14:15], v[4:5]
	v_and_b32_e32 v15, 0x7fffffff, v3
	v_and_b32_e32 v14, 0x7fffffff, v2
	v_pk_fma_f32 v[14:15], v[14:15], s[26:27], 1.0 op_sel_hi:[1,0,0]
	v_pk_mul_f32 v[4:5], v[6:7], v[4:5]
	v_rcp_f32_e32 v14, v14
	v_rcp_f32_e32 v15, v15
	v_max_f32_e32 v6, 0, v0
	v_max_f32_e32 v7, 0, v1
	v_fma_f32 v6, -|v0|, v4, v6
	v_fma_f32 v7, -|v1|, v5, v7
	v_pk_mul_f32 v[10:11], v[2:3], v[2:3]
	v_pk_fma_f32 v[0:1], v[14:15], s[28:29], v[8:9] op_sel_hi:[1,0,0]
	s_nop 0
	v_pk_mul_f32 v[4:5], v[10:11], s[40:41] op_sel_hi:[1,0]
	v_pk_fma_f32 v[0:1], v[14:15], v[0:1], s[34:35] op_sel_hi:[1,1,0]
	v_exp_f32_e32 v4, v4
	v_exp_f32_e32 v5, v5
	v_pk_fma_f32 v[0:1], v[14:15], v[0:1], s[36:37] op_sel_hi:[1,1,0]
	v_cmp_gt_f32_e32 vcc, 0, v2
	v_pk_fma_f32 v[0:1], v[14:15], v[0:1], s[38:39] op_sel_hi:[1,1,0]
	s_nop 0
	v_pk_mul_f32 v[0:1], v[14:15], v[0:1]
	s_nop 0
	v_pk_mul_f32 v[0:1], v[4:5], v[0:1]
	s_nop 0
	v_pk_mul_f32 v[4:5], v[2:3], v[0:1]
	v_pk_fma_f32 v[0:1], v[2:3], v[0:1], v[2:3] neg_lo:[1,0,0] neg_hi:[1,0,0]
	s_nop 0
	v_cndmask_b32_e32 v4, v0, v4, vcc
	v_cmp_gt_f32_e32 vcc, 0, v3
	v_cvt_pk_bf16_f32 v0, v18, v19
	s_nop 1
	v_cndmask_b32_e32 v3, v1, v5, vcc
	s_and_b64 vcc, exec, s[8:9]
	v_cvt_pk_bf16_f32 v1, v20, v21
	v_cvt_pk_bf16_f32 v2, v6, v7
	v_cvt_pk_bf16_f32 v3, v4, v3
	global_store_dwordx4 v[16:17], v[0:3], off offset:256
	s_cbranch_vccnz .LBB0_271
	v_lshlrev_b32_e32 v4, 16, v0
	v_and_b32_e32 v0, 0xffff0000, v0
	v_lshlrev_b32_e32 v6, 16, v1
	v_and_b32_e32 v8, 0xffff0000, v1
	v_lshlrev_b32_e32 v10, 16, v2
	v_and_b32_e32 v2, 0xffff0000, v2
	v_lshlrev_b32_e32 v14, 16, v3
	v_and_b32_e32 v16, 0xffff0000, v3
	v_mul_f32_e32 v5, v4, v4
	v_mul_f32_e32 v1, v0, v0
	v_mul_f32_e32 v7, v6, v6
	v_mul_f32_e32 v9, v8, v8
	v_mul_f32_e32 v11, v10, v10
	v_mul_f32_e32 v3, v2, v2
	v_mul_f32_e32 v15, v14, v14
	v_mul_f32_e32 v17, v16, v16
	v_pk_add_f32 v[0:1], v[4:5], v[0:1]
	v_pk_add_f32 v[4:5], v[6:7], v[8:9]
	v_pk_add_f32 v[2:3], v[10:11], v[2:3]
	v_pk_add_f32 v[0:1], v[0:1], v[4:5]
	v_pk_add_f32 v[4:5], v[14:15], v[16:17]
	s_nop 0
	v_pk_add_f32 v[2:3], v[2:3], v[4:5]
	s_nop 0
	v_pk_add_f32 v[0:1], v[0:1], v[2:3]
	s_nop 0
	v_pk_add_f32 v[0:1], v[12:13], v[0:1]
	s_nop 0
	v_mov_b32_e32 v2, v0
	v_mov_b32_e32 v3, v1
	s_nop 0
	v_permlane16_swap_b32_e32 v0, v2
	v_permlane16_swap_b32_e32 v1, v3
	v_pk_add_f32 v[0:1], v[0:1], v[2:3]
	s_nop 0
	v_mov_b32_e32 v2, v0
	v_mov_b32_e32 v3, v1
	s_nop 0
	v_permlane32_swap_b32_e32 v0, v2
	v_permlane32_swap_b32_e32 v1, v3
	v_pk_add_f32 v[0:1], v[0:1], v[2:3]
	s_and_saveexec_b64 s[8:9], s[4:5]
	s_cbranch_execz .LBB0_270
	v_lshlrev_b64 v[4:5], 8, v[148:149]
	v_lshl_add_u64 v[4:5], s[16:17], 0, v[4:5]
	v_lshl_add_u64 v[4:5], s[50:51], 2, v[4:5]
	global_store_dwordx2 v[4:5], v[0:1], off
